# P1 and P7 row reductions: first four butterfly steps with DPP adds, only the two cross-row steps through ds_bpermute
# speedup vs baseline: 1.0007x; 1.0007x over previous
.Lp1n_nope_a0:
	v_pk_mul_f32 v[34:35], v[84:85], v[84:85]
	v_pk_mul_f32 v[36:37], v[100:101], v[100:101]
	v_pk_mul_f32 v[38:39], v[116:117], v[116:117]
	v_pk_mul_f32 v[40:41], v[132:133], v[132:133]
	v_pk_fma_f32 v[34:35], v[86:87], v[86:87], v[34:35]
	v_pk_fma_f32 v[36:37], v[102:103], v[102:103], v[36:37]
	v_pk_fma_f32 v[38:39], v[118:119], v[118:119], v[38:39]
	v_pk_fma_f32 v[40:41], v[134:135], v[134:135], v[40:41]
	v_pk_fma_f32 v[34:35], v[88:89], v[88:89], v[34:35]
	v_pk_fma_f32 v[36:37], v[104:105], v[104:105], v[36:37]
	v_pk_fma_f32 v[38:39], v[120:121], v[120:121], v[38:39]
	v_pk_fma_f32 v[40:41], v[136:137], v[136:137], v[40:41]
	v_pk_fma_f32 v[34:35], v[90:91], v[90:91], v[34:35]
	v_pk_fma_f32 v[36:37], v[106:107], v[106:107], v[36:37]
	v_pk_fma_f32 v[38:39], v[122:123], v[122:123], v[38:39]
	v_pk_fma_f32 v[40:41], v[138:139], v[138:139], v[40:41]
	v_pk_fma_f32 v[34:35], v[92:93], v[92:93], v[34:35]
	v_pk_fma_f32 v[36:37], v[108:109], v[108:109], v[36:37]
	v_pk_fma_f32 v[38:39], v[124:125], v[124:125], v[38:39]
	v_pk_fma_f32 v[40:41], v[140:141], v[140:141], v[40:41]
	v_pk_fma_f32 v[34:35], v[94:95], v[94:95], v[34:35]
	v_pk_fma_f32 v[36:37], v[110:111], v[110:111], v[36:37]
	v_pk_fma_f32 v[38:39], v[126:127], v[126:127], v[38:39]
	v_pk_fma_f32 v[40:41], v[142:143], v[142:143], v[40:41]
	v_pk_fma_f32 v[34:35], v[96:97], v[96:97], v[34:35]
	v_pk_fma_f32 v[36:37], v[112:113], v[112:113], v[36:37]
	v_pk_fma_f32 v[38:39], v[128:129], v[128:129], v[38:39]
	v_pk_fma_f32 v[40:41], v[144:145], v[144:145], v[40:41]
	v_pk_fma_f32 v[34:35], v[98:99], v[98:99], v[34:35]
	v_pk_fma_f32 v[36:37], v[114:115], v[114:115], v[36:37]
	v_pk_fma_f32 v[38:39], v[130:131], v[130:131], v[38:39]
	v_pk_fma_f32 v[40:41], v[146:147], v[146:147], v[40:41]
	v_add_f32_e32 v34, v34, v35
	v_add_f32_e32 v36, v36, v37
	v_add_f32_e32 v38, v38, v39
	v_add_f32_e32 v40, v40, v41
	v_add_f32_dpp v34, v34, v34 quad_perm:[1,0,3,2] row_mask:0xf bank_mask:0xf
	v_add_f32_dpp v36, v36, v36 quad_perm:[1,0,3,2] row_mask:0xf bank_mask:0xf
	v_add_f32_dpp v38, v38, v38 quad_perm:[1,0,3,2] row_mask:0xf bank_mask:0xf
	v_add_f32_dpp v40, v40, v40 quad_perm:[1,0,3,2] row_mask:0xf bank_mask:0xf
	v_add_f32_dpp v34, v34, v34 quad_perm:[2,3,0,1] row_mask:0xf bank_mask:0xf
	v_add_f32_dpp v36, v36, v36 quad_perm:[2,3,0,1] row_mask:0xf bank_mask:0xf
	v_add_f32_dpp v38, v38, v38 quad_perm:[2,3,0,1] row_mask:0xf bank_mask:0xf
	v_add_f32_dpp v40, v40, v40 quad_perm:[2,3,0,1] row_mask:0xf bank_mask:0xf
	v_add_f32_dpp v34, v34, v34 row_ror:4 row_mask:0xf bank_mask:0xf
	v_add_f32_dpp v36, v36, v36 row_ror:4 row_mask:0xf bank_mask:0xf
	v_add_f32_dpp v38, v38, v38 row_ror:4 row_mask:0xf bank_mask:0xf
	v_add_f32_dpp v40, v40, v40 row_ror:4 row_mask:0xf bank_mask:0xf
	v_add_f32_dpp v34, v34, v34 row_ror:8 row_mask:0xf bank_mask:0xf
	v_add_f32_dpp v36, v36, v36 row_ror:8 row_mask:0xf bank_mask:0xf
	v_add_f32_dpp v38, v38, v38 row_ror:8 row_mask:0xf bank_mask:0xf
	v_add_f32_dpp v40, v40, v40 row_ror:8 row_mask:0xf bank_mask:0xf
	ds_bpermute_b32 v35, v69, v34
	ds_bpermute_b32 v37, v69, v36
	ds_bpermute_b32 v39, v69, v38
	ds_bpermute_b32 v41, v69, v40
	s_waitcnt lgkmcnt(0)
	v_add_f32_e32 v34, v34, v35
	v_add_f32_e32 v36, v36, v37
	v_add_f32_e32 v38, v38, v39
	v_add_f32_e32 v40, v40, v41
	ds_bpermute_b32 v35, v70, v34
	ds_bpermute_b32 v37, v70, v36
	ds_bpermute_b32 v39, v70, v38
	ds_bpermute_b32 v41, v70, v40
	s_waitcnt lgkmcnt(0)
	v_add_f32_e32 v34, v34, v35
	v_add_f32_e32 v36, v36, v37
	v_add_f32_e32 v38, v38, v39
	v_add_f32_e32 v40, v40, v41
	v_fmamk_f32 v34, v34, 0x3a800000, v74
	v_fmamk_f32 v36, v36, 0x3a800000, v74
	v_fmamk_f32 v38, v38, 0x3a800000, v74
	v_fmamk_f32 v40, v40, 0x3a800000, v74
	v_mul_f32_e32 v75, 0x4b800000, v34
	v_cmp_gt_f32_e32 vcc, s24, v34
	s_nop 1
	v_cndmask_b32_e32 v34, v34, v75, vcc
	v_rsq_f32_e32 v34, v34
	s_nop 0
	v_mul_f32_e32 v75, 0x45800000, v34
	v_cndmask_b32_e32 v34, v34, v75, vcc
	v_mov_b32_e32 v35, 0
	v_mul_f32_e32 v75, 0x4b800000, v36
	v_cmp_gt_f32_e32 vcc, s24, v36
	s_nop 1
	v_cndmask_b32_e32 v36, v36, v75, vcc
	v_rsq_f32_e32 v36, v36
	s_nop 0
	v_mul_f32_e32 v75, 0x45800000, v36
	v_cndmask_b32_e32 v36, v36, v75, vcc
	v_mov_b32_e32 v37, 0
	v_mul_f32_e32 v75, 0x4b800000, v38
	v_cmp_gt_f32_e32 vcc, s24, v38
	s_nop 1
	v_cndmask_b32_e32 v38, v38, v75, vcc
	v_rsq_f32_e32 v38, v38
	s_nop 0
	v_mul_f32_e32 v75, 0x45800000, v38
	v_cndmask_b32_e32 v38, v38, v75, vcc
	v_mov_b32_e32 v39, 0
	v_mul_f32_e32 v75, 0x4b800000, v40
	v_cmp_gt_f32_e32 vcc, s24, v40
	s_nop 1
	v_cndmask_b32_e32 v40, v40, v75, vcc
	v_rsq_f32_e32 v40, v40
	s_nop 0
	v_mul_f32_e32 v75, 0x45800000, v40
	v_cndmask_b32_e32 v40, v40, v75, vcc
	v_mov_b32_e32 v41, 0
	s_add_u32 s0, s19, 0
	s_lshl_b32 s0, s0, 11
	s_add_u32 s2, s72, s0
	s_addc_u32 s3, s73, 0
	v_pk_mul_f32 v[84:85], v[84:85], v[34:35] op_sel_hi:[1,0]
	v_pk_mul_f32 v[86:87], v[86:87], v[34:35] op_sel_hi:[1,0]
	v_pk_fma_f32 v[84:85], v[2:3], v[84:85], v[10:11]
	v_pk_fma_f32 v[86:87], v[4:5], v[86:87], v[12:13]
	v_cvt_pk_bf16_f32 v84, v84, v85
	v_cvt_pk_bf16_f32 v85, v86, v87
	global_store_dwordx2 v78, v[84:85], s[2:3] offset:0
	v_pk_mul_f32 v[88:89], v[88:89], v[34:35] op_sel_hi:[1,0]
	v_pk_mul_f32 v[90:91], v[90:91], v[34:35] op_sel_hi:[1,0]
	v_pk_fma_f32 v[88:89], v[6:7], v[88:89], v[14:15]
	v_pk_fma_f32 v[90:91], v[8:9], v[90:91], v[16:17]
	v_cvt_pk_bf16_f32 v88, v88, v89
	v_cvt_pk_bf16_f32 v89, v90, v91
	global_store_dwordx2 v78, v[88:89], s[2:3] offset:512
	v_pk_mul_f32 v[92:93], v[92:93], v[34:35] op_sel_hi:[1,0]
	v_pk_mul_f32 v[94:95], v[94:95], v[34:35] op_sel_hi:[1,0]
	v_pk_fma_f32 v[92:93], v[18:19], v[92:93], v[26:27]
	v_pk_fma_f32 v[94:95], v[20:21], v[94:95], v[28:29]
	v_cvt_pk_bf16_f32 v92, v92, v93
	v_cvt_pk_bf16_f32 v93, v94, v95
	global_store_dwordx2 v78, v[92:93], s[2:3] offset:1024
	v_pk_mul_f32 v[96:97], v[96:97], v[34:35] op_sel_hi:[1,0]
	v_pk_mul_f32 v[98:99], v[98:99], v[34:35] op_sel_hi:[1,0]
	v_pk_fma_f32 v[96:97], v[22:23], v[96:97], v[30:31]
	v_pk_fma_f32 v[98:99], v[24:25], v[98:99], v[32:33]
	v_cvt_pk_bf16_f32 v96, v96, v97
	v_cvt_pk_bf16_f32 v97, v98, v99
	global_store_dwordx2 v78, v[96:97], s[2:3] offset:1536
	s_add_u32 s0, s19, 1
	s_lshl_b32 s0, s0, 11
	s_add_u32 s2, s72, s0
	s_addc_u32 s3, s73, 0
	v_pk_mul_f32 v[100:101], v[100:101], v[36:37] op_sel_hi:[1,0]
	v_pk_mul_f32 v[102:103], v[102:103], v[36:37] op_sel_hi:[1,0]
	v_pk_fma_f32 v[100:101], v[2:3], v[100:101], v[10:11]
	v_pk_fma_f32 v[102:103], v[4:5], v[102:103], v[12:13]
	v_cvt_pk_bf16_f32 v100, v100, v101
	v_cvt_pk_bf16_f32 v101, v102, v103
	global_store_dwordx2 v78, v[100:101], s[2:3] offset:0
	v_pk_mul_f32 v[104:105], v[104:105], v[36:37] op_sel_hi:[1,0]
	v_pk_mul_f32 v[106:107], v[106:107], v[36:37] op_sel_hi:[1,0]
	v_pk_fma_f32 v[104:105], v[6:7], v[104:105], v[14:15]
	v_pk_fma_f32 v[106:107], v[8:9], v[106:107], v[16:17]
	v_cvt_pk_bf16_f32 v104, v104, v105
	v_cvt_pk_bf16_f32 v105, v106, v107
	global_store_dwordx2 v78, v[104:105], s[2:3] offset:512
	v_pk_mul_f32 v[108:109], v[108:109], v[36:37] op_sel_hi:[1,0]
	v_pk_mul_f32 v[110:111], v[110:111], v[36:37] op_sel_hi:[1,0]
	v_pk_fma_f32 v[108:109], v[18:19], v[108:109], v[26:27]
	v_pk_fma_f32 v[110:111], v[20:21], v[110:111], v[28:29]
	v_cvt_pk_bf16_f32 v108, v108, v109
	v_cvt_pk_bf16_f32 v109, v110, v111
	global_store_dwordx2 v78, v[108:109], s[2:3] offset:1024
	v_pk_mul_f32 v[112:113], v[112:113], v[36:37] op_sel_hi:[1,0]
	v_pk_mul_f32 v[114:115], v[114:115], v[36:37] op_sel_hi:[1,0]
	v_pk_fma_f32 v[112:113], v[22:23], v[112:113], v[30:31]
	v_pk_fma_f32 v[114:115], v[24:25], v[114:115], v[32:33]
	v_cvt_pk_bf16_f32 v112, v112, v113
	v_cvt_pk_bf16_f32 v113, v114, v115
	global_store_dwordx2 v78, v[112:113], s[2:3] offset:1536
	s_add_u32 s0, s19, 2
	s_lshl_b32 s0, s0, 11
	s_add_u32 s2, s72, s0
	s_addc_u32 s3, s73, 0
	v_pk_mul_f32 v[116:117], v[116:117], v[38:39] op_sel_hi:[1,0]
	v_pk_mul_f32 v[118:119], v[118:119], v[38:39] op_sel_hi:[1,0]
	v_pk_fma_f32 v[116:117], v[2:3], v[116:117], v[10:11]
	v_pk_fma_f32 v[118:119], v[4:5], v[118:119], v[12:13]
	v_cvt_pk_bf16_f32 v116, v116, v117
	v_cvt_pk_bf16_f32 v117, v118, v119
	global_store_dwordx2 v78, v[116:117], s[2:3] offset:0
	v_pk_mul_f32 v[120:121], v[120:121], v[38:39] op_sel_hi:[1,0]
	v_pk_mul_f32 v[122:123], v[122:123], v[38:39] op_sel_hi:[1,0]
	v_pk_fma_f32 v[120:121], v[6:7], v[120:121], v[14:15]
	v_pk_fma_f32 v[122:123], v[8:9], v[122:123], v[16:17]
	v_cvt_pk_bf16_f32 v120, v120, v121
	v_cvt_pk_bf16_f32 v121, v122, v123
	global_store_dwordx2 v78, v[120:121], s[2:3] offset:512
	v_pk_mul_f32 v[124:125], v[124:125], v[38:39] op_sel_hi:[1,0]
	v_pk_mul_f32 v[126:127], v[126:127], v[38:39] op_sel_hi:[1,0]
	v_pk_fma_f32 v[124:125], v[18:19], v[124:125], v[26:27]
	v_pk_fma_f32 v[126:127], v[20:21], v[126:127], v[28:29]
	v_cvt_pk_bf16_f32 v124, v124, v125
	v_cvt_pk_bf16_f32 v125, v126, v127
	global_store_dwordx2 v78, v[124:125], s[2:3] offset:1024
	v_pk_mul_f32 v[128:129], v[128:129], v[38:39] op_sel_hi:[1,0]
	v_pk_mul_f32 v[130:131], v[130:131], v[38:39] op_sel_hi:[1,0]
	v_pk_fma_f32 v[128:129], v[22:23], v[128:129], v[30:31]
	v_pk_fma_f32 v[130:131], v[24:25], v[130:131], v[32:33]
	v_cvt_pk_bf16_f32 v128, v128, v129
	v_cvt_pk_bf16_f32 v129, v130, v131
	global_store_dwordx2 v78, v[128:129], s[2:3] offset:1536
	s_add_u32 s0, s19, 3
	s_lshl_b32 s0, s0, 11
	s_add_u32 s2, s72, s0
	s_addc_u32 s3, s73, 0
	v_pk_mul_f32 v[132:133], v[132:133], v[40:41] op_sel_hi:[1,0]
	v_pk_mul_f32 v[134:135], v[134:135], v[40:41] op_sel_hi:[1,0]
	v_pk_fma_f32 v[132:133], v[2:3], v[132:133], v[10:11]
	v_pk_fma_f32 v[134:135], v[4:5], v[134:135], v[12:13]
	v_cvt_pk_bf16_f32 v132, v132, v133
	v_cvt_pk_bf16_f32 v133, v134, v135
	global_store_dwordx2 v78, v[132:133], s[2:3] offset:0
	v_pk_mul_f32 v[136:137], v[136:137], v[40:41] op_sel_hi:[1,0]
	v_pk_mul_f32 v[138:139], v[138:139], v[40:41] op_sel_hi:[1,0]
	v_pk_fma_f32 v[136:137], v[6:7], v[136:137], v[14:15]
	v_pk_fma_f32 v[138:139], v[8:9], v[138:139], v[16:17]
	v_cvt_pk_bf16_f32 v136, v136, v137
	v_cvt_pk_bf16_f32 v137, v138, v139
	global_store_dwordx2 v78, v[136:137], s[2:3] offset:512
	v_pk_mul_f32 v[140:141], v[140:141], v[40:41] op_sel_hi:[1,0]
	v_pk_mul_f32 v[142:143], v[142:143], v[40:41] op_sel_hi:[1,0]
	v_pk_fma_f32 v[140:141], v[18:19], v[140:141], v[26:27]
	v_pk_fma_f32 v[142:143], v[20:21], v[142:143], v[28:29]
	v_cvt_pk_bf16_f32 v140, v140, v141
	v_cvt_pk_bf16_f32 v141, v142, v143
	global_store_dwordx2 v78, v[140:141], s[2:3] offset:1024
	v_pk_mul_f32 v[144:145], v[144:145], v[40:41] op_sel_hi:[1,0]
	v_pk_mul_f32 v[146:147], v[146:147], v[40:41] op_sel_hi:[1,0]
	v_pk_fma_f32 v[144:145], v[22:23], v[144:145], v[30:31]
	v_pk_fma_f32 v[146:147], v[24:25], v[146:147], v[32:33]
	v_cvt_pk_bf16_f32 v144, v144, v145
	v_cvt_pk_bf16_f32 v145, v146, v147
	global_store_dwordx2 v78, v[144:145], s[2:3] offset:1536
	s_nop 1
	s_add_u32 s0, s19, 4
	s_cmpk_lt_u32 s0, 0x2000
	s_cselect_b32 s2, s8, s10
	s_cselect_b32 s3, s9, s11
	s_and_b32 s1, s0, 0x1fff
	s_lshl_b32 s4, s1, 12
	s_add_u32 s2, s2, s4
	s_addc_u32 s3, s3, 0
	global_load_dwordx4 v[84:87], v52, s[2:3] offset:0 nt
	global_load_dwordx4 v[88:91], v52, s[2:3] offset:1024 nt
	global_load_dwordx4 v[92:95], v52, s[2:3] offset:2048 nt
	global_load_dwordx4 v[96:99], v52, s[2:3] offset:3072 nt
	s_cmp_eq_u32 s26, 0
	s_cbranch_scc1 .Lp1n_nocol_a4
	s_and_b32 s4, s0, 63
	s_lshl_b32 s4, s4, 10
	s_add_u32 s2, s74, 0x94000
	s_addc_u32 s3, s75, 0
	s_add_u32 s2, s2, s4
	s_addc_u32 s3, s3, 0
	global_load_dwordx4 v[148:151], v52, s[2:3]
	s_add_u32 s2, s2, 0x10000
	s_addc_u32 s3, s3, 0
	global_load_dwordx4 v[152:155], v52, s[2:3]

.Lp1n_nope_a1:
	v_pk_mul_f32 v[34:35], v[84:85], v[84:85]
	v_pk_mul_f32 v[36:37], v[100:101], v[100:101]
	v_pk_mul_f32 v[38:39], v[116:117], v[116:117]
	v_pk_mul_f32 v[40:41], v[132:133], v[132:133]
	v_pk_fma_f32 v[34:35], v[86:87], v[86:87], v[34:35]
	v_pk_fma_f32 v[36:37], v[102:103], v[102:103], v[36:37]
	v_pk_fma_f32 v[38:39], v[118:119], v[118:119], v[38:39]
	v_pk_fma_f32 v[40:41], v[134:135], v[134:135], v[40:41]
	v_pk_fma_f32 v[34:35], v[88:89], v[88:89], v[34:35]
	v_pk_fma_f32 v[36:37], v[104:105], v[104:105], v[36:37]
	v_pk_fma_f32 v[38:39], v[120:121], v[120:121], v[38:39]
	v_pk_fma_f32 v[40:41], v[136:137], v[136:137], v[40:41]
	v_pk_fma_f32 v[34:35], v[90:91], v[90:91], v[34:35]
	v_pk_fma_f32 v[36:37], v[106:107], v[106:107], v[36:37]
	v_pk_fma_f32 v[38:39], v[122:123], v[122:123], v[38:39]
	v_pk_fma_f32 v[40:41], v[138:139], v[138:139], v[40:41]
	v_pk_fma_f32 v[34:35], v[92:93], v[92:93], v[34:35]
	v_pk_fma_f32 v[36:37], v[108:109], v[108:109], v[36:37]
	v_pk_fma_f32 v[38:39], v[124:125], v[124:125], v[38:39]
	v_pk_fma_f32 v[40:41], v[140:141], v[140:141], v[40:41]
	v_pk_fma_f32 v[34:35], v[94:95], v[94:95], v[34:35]
	v_pk_fma_f32 v[36:37], v[110:111], v[110:111], v[36:37]
	v_pk_fma_f32 v[38:39], v[126:127], v[126:127], v[38:39]
	v_pk_fma_f32 v[40:41], v[142:143], v[142:143], v[40:41]
	v_pk_fma_f32 v[34:35], v[96:97], v[96:97], v[34:35]
	v_pk_fma_f32 v[36:37], v[112:113], v[112:113], v[36:37]
	v_pk_fma_f32 v[38:39], v[128:129], v[128:129], v[38:39]
	v_pk_fma_f32 v[40:41], v[144:145], v[144:145], v[40:41]
	v_pk_fma_f32 v[34:35], v[98:99], v[98:99], v[34:35]
	v_pk_fma_f32 v[36:37], v[114:115], v[114:115], v[36:37]
	v_pk_fma_f32 v[38:39], v[130:131], v[130:131], v[38:39]
	v_pk_fma_f32 v[40:41], v[146:147], v[146:147], v[40:41]
	v_add_f32_e32 v34, v34, v35
	v_add_f32_e32 v36, v36, v37
	v_add_f32_e32 v38, v38, v39
	v_add_f32_e32 v40, v40, v41
	v_add_f32_dpp v34, v34, v34 quad_perm:[1,0,3,2] row_mask:0xf bank_mask:0xf
	v_add_f32_dpp v36, v36, v36 quad_perm:[1,0,3,2] row_mask:0xf bank_mask:0xf
	v_add_f32_dpp v38, v38, v38 quad_perm:[1,0,3,2] row_mask:0xf bank_mask:0xf
	v_add_f32_dpp v40, v40, v40 quad_perm:[1,0,3,2] row_mask:0xf bank_mask:0xf
	v_add_f32_dpp v34, v34, v34 quad_perm:[2,3,0,1] row_mask:0xf bank_mask:0xf
	v_add_f32_dpp v36, v36, v36 quad_perm:[2,3,0,1] row_mask:0xf bank_mask:0xf
	v_add_f32_dpp v38, v38, v38 quad_perm:[2,3,0,1] row_mask:0xf bank_mask:0xf
	v_add_f32_dpp v40, v40, v40 quad_perm:[2,3,0,1] row_mask:0xf bank_mask:0xf
	v_add_f32_dpp v34, v34, v34 row_ror:4 row_mask:0xf bank_mask:0xf
	v_add_f32_dpp v36, v36, v36 row_ror:4 row_mask:0xf bank_mask:0xf
	v_add_f32_dpp v38, v38, v38 row_ror:4 row_mask:0xf bank_mask:0xf
	v_add_f32_dpp v40, v40, v40 row_ror:4 row_mask:0xf bank_mask:0xf
	v_add_f32_dpp v34, v34, v34 row_ror:8 row_mask:0xf bank_mask:0xf
	v_add_f32_dpp v36, v36, v36 row_ror:8 row_mask:0xf bank_mask:0xf
	v_add_f32_dpp v38, v38, v38 row_ror:8 row_mask:0xf bank_mask:0xf
	v_add_f32_dpp v40, v40, v40 row_ror:8 row_mask:0xf bank_mask:0xf
	ds_bpermute_b32 v35, v69, v34
	ds_bpermute_b32 v37, v69, v36
	ds_bpermute_b32 v39, v69, v38
	ds_bpermute_b32 v41, v69, v40
	s_waitcnt lgkmcnt(0)
	v_add_f32_e32 v34, v34, v35
	v_add_f32_e32 v36, v36, v37
	v_add_f32_e32 v38, v38, v39
	v_add_f32_e32 v40, v40, v41
	ds_bpermute_b32 v35, v70, v34
	ds_bpermute_b32 v37, v70, v36
	ds_bpermute_b32 v39, v70, v38
	ds_bpermute_b32 v41, v70, v40
	s_waitcnt lgkmcnt(0)
	v_add_f32_e32 v34, v34, v35
	v_add_f32_e32 v36, v36, v37
	v_add_f32_e32 v38, v38, v39
	v_add_f32_e32 v40, v40, v41
	v_fmamk_f32 v34, v34, 0x3a800000, v74
	v_fmamk_f32 v36, v36, 0x3a800000, v74
	v_fmamk_f32 v38, v38, 0x3a800000, v74
	v_fmamk_f32 v40, v40, 0x3a800000, v74
	v_mul_f32_e32 v75, 0x4b800000, v34
	v_cmp_gt_f32_e32 vcc, s24, v34
	s_nop 1
	v_cndmask_b32_e32 v34, v34, v75, vcc
	v_rsq_f32_e32 v34, v34
	s_nop 0
	v_mul_f32_e32 v75, 0x45800000, v34
	v_cndmask_b32_e32 v34, v34, v75, vcc
	v_mov_b32_e32 v35, 0
	v_mul_f32_e32 v75, 0x4b800000, v36
	v_cmp_gt_f32_e32 vcc, s24, v36
	s_nop 1
	v_cndmask_b32_e32 v36, v36, v75, vcc
	v_rsq_f32_e32 v36, v36
	s_nop 0
	v_mul_f32_e32 v75, 0x45800000, v36
	v_cndmask_b32_e32 v36, v36, v75, vcc
	v_mov_b32_e32 v37, 0
	v_mul_f32_e32 v75, 0x4b800000, v38
	v_cmp_gt_f32_e32 vcc, s24, v38
	s_nop 1
	v_cndmask_b32_e32 v38, v38, v75, vcc
	v_rsq_f32_e32 v38, v38
	s_nop 0
	v_mul_f32_e32 v75, 0x45800000, v38
	v_cndmask_b32_e32 v38, v38, v75, vcc
	v_mov_b32_e32 v39, 0
	v_mul_f32_e32 v75, 0x4b800000, v40
	v_cmp_gt_f32_e32 vcc, s24, v40
	s_nop 1
	v_cndmask_b32_e32 v40, v40, v75, vcc
	v_rsq_f32_e32 v40, v40
	s_nop 0
	v_mul_f32_e32 v75, 0x45800000, v40
	v_cndmask_b32_e32 v40, v40, v75, vcc
	v_mov_b32_e32 v41, 0
	s_add_u32 s0, s19, 4
	s_lshl_b32 s0, s0, 11
	s_add_u32 s2, s72, s0
	s_addc_u32 s3, s73, 0
	v_pk_mul_f32 v[84:85], v[84:85], v[34:35] op_sel_hi:[1,0]
	v_pk_mul_f32 v[86:87], v[86:87], v[34:35] op_sel_hi:[1,0]
	v_pk_fma_f32 v[84:85], v[2:3], v[84:85], v[10:11]
	v_pk_fma_f32 v[86:87], v[4:5], v[86:87], v[12:13]
	v_cvt_pk_bf16_f32 v84, v84, v85
	v_cvt_pk_bf16_f32 v85, v86, v87
	global_store_dwordx2 v78, v[84:85], s[2:3] offset:0
	v_pk_mul_f32 v[88:89], v[88:89], v[34:35] op_sel_hi:[1,0]
	v_pk_mul_f32 v[90:91], v[90:91], v[34:35] op_sel_hi:[1,0]
	v_pk_fma_f32 v[88:89], v[6:7], v[88:89], v[14:15]
	v_pk_fma_f32 v[90:91], v[8:9], v[90:91], v[16:17]
	v_cvt_pk_bf16_f32 v88, v88, v89
	v_cvt_pk_bf16_f32 v89, v90, v91
	global_store_dwordx2 v78, v[88:89], s[2:3] offset:512
	v_pk_mul_f32 v[92:93], v[92:93], v[34:35] op_sel_hi:[1,0]
	v_pk_mul_f32 v[94:95], v[94:95], v[34:35] op_sel_hi:[1,0]
	v_pk_fma_f32 v[92:93], v[18:19], v[92:93], v[26:27]
	v_pk_fma_f32 v[94:95], v[20:21], v[94:95], v[28:29]
	v_cvt_pk_bf16_f32 v92, v92, v93
	v_cvt_pk_bf16_f32 v93, v94, v95
	global_store_dwordx2 v78, v[92:93], s[2:3] offset:1024
	v_pk_mul_f32 v[96:97], v[96:97], v[34:35] op_sel_hi:[1,0]
	v_pk_mul_f32 v[98:99], v[98:99], v[34:35] op_sel_hi:[1,0]
	v_pk_fma_f32 v[96:97], v[22:23], v[96:97], v[30:31]
	v_pk_fma_f32 v[98:99], v[24:25], v[98:99], v[32:33]
	v_cvt_pk_bf16_f32 v96, v96, v97
	v_cvt_pk_bf16_f32 v97, v98, v99
	global_store_dwordx2 v78, v[96:97], s[2:3] offset:1536
	s_add_u32 s0, s19, 5
	s_lshl_b32 s0, s0, 11
	s_add_u32 s2, s72, s0
	s_addc_u32 s3, s73, 0
	v_pk_mul_f32 v[100:101], v[100:101], v[36:37] op_sel_hi:[1,0]
	v_pk_mul_f32 v[102:103], v[102:103], v[36:37] op_sel_hi:[1,0]
	v_pk_fma_f32 v[100:101], v[2:3], v[100:101], v[10:11]
	v_pk_fma_f32 v[102:103], v[4:5], v[102:103], v[12:13]
	v_cvt_pk_bf16_f32 v100, v100, v101
	v_cvt_pk_bf16_f32 v101, v102, v103
	global_store_dwordx2 v78, v[100:101], s[2:3] offset:0
	v_pk_mul_f32 v[104:105], v[104:105], v[36:37] op_sel_hi:[1,0]
	v_pk_mul_f32 v[106:107], v[106:107], v[36:37] op_sel_hi:[1,0]
	v_pk_fma_f32 v[104:105], v[6:7], v[104:105], v[14:15]
	v_pk_fma_f32 v[106:107], v[8:9], v[106:107], v[16:17]
	v_cvt_pk_bf16_f32 v104, v104, v105
	v_cvt_pk_bf16_f32 v105, v106, v107
	global_store_dwordx2 v78, v[104:105], s[2:3] offset:512
	v_pk_mul_f32 v[108:109], v[108:109], v[36:37] op_sel_hi:[1,0]
	v_pk_mul_f32 v[110:111], v[110:111], v[36:37] op_sel_hi:[1,0]
	v_pk_fma_f32 v[108:109], v[18:19], v[108:109], v[26:27]
	v_pk_fma_f32 v[110:111], v[20:21], v[110:111], v[28:29]
	v_cvt_pk_bf16_f32 v108, v108, v109
	v_cvt_pk_bf16_f32 v109, v110, v111
	global_store_dwordx2 v78, v[108:109], s[2:3] offset:1024
	v_pk_mul_f32 v[112:113], v[112:113], v[36:37] op_sel_hi:[1,0]
	v_pk_mul_f32 v[114:115], v[114:115], v[36:37] op_sel_hi:[1,0]
	v_pk_fma_f32 v[112:113], v[22:23], v[112:113], v[30:31]
	v_pk_fma_f32 v[114:115], v[24:25], v[114:115], v[32:33]
	v_cvt_pk_bf16_f32 v112, v112, v113
	v_cvt_pk_bf16_f32 v113, v114, v115
	global_store_dwordx2 v78, v[112:113], s[2:3] offset:1536
	s_add_u32 s0, s19, 6
	s_lshl_b32 s0, s0, 11
	s_add_u32 s2, s72, s0
	s_addc_u32 s3, s73, 0
	v_pk_mul_f32 v[116:117], v[116:117], v[38:39] op_sel_hi:[1,0]
	v_pk_mul_f32 v[118:119], v[118:119], v[38:39] op_sel_hi:[1,0]
	v_pk_fma_f32 v[116:117], v[2:3], v[116:117], v[10:11]
	v_pk_fma_f32 v[118:119], v[4:5], v[118:119], v[12:13]
	v_cvt_pk_bf16_f32 v116, v116, v117
	v_cvt_pk_bf16_f32 v117, v118, v119
	global_store_dwordx2 v78, v[116:117], s[2:3] offset:0
	v_pk_mul_f32 v[120:121], v[120:121], v[38:39] op_sel_hi:[1,0]
	v_pk_mul_f32 v[122:123], v[122:123], v[38:39] op_sel_hi:[1,0]
	v_pk_fma_f32 v[120:121], v[6:7], v[120:121], v[14:15]
	v_pk_fma_f32 v[122:123], v[8:9], v[122:123], v[16:17]
	v_cvt_pk_bf16_f32 v120, v120, v121
	v_cvt_pk_bf16_f32 v121, v122, v123
	global_store_dwordx2 v78, v[120:121], s[2:3] offset:512
	v_pk_mul_f32 v[124:125], v[124:125], v[38:39] op_sel_hi:[1,0]
	v_pk_mul_f32 v[126:127], v[126:127], v[38:39] op_sel_hi:[1,0]
	v_pk_fma_f32 v[124:125], v[18:19], v[124:125], v[26:27]
	v_pk_fma_f32 v[126:127], v[20:21], v[126:127], v[28:29]
	v_cvt_pk_bf16_f32 v124, v124, v125
	v_cvt_pk_bf16_f32 v125, v126, v127
	global_store_dwordx2 v78, v[124:125], s[2:3] offset:1024
	v_pk_mul_f32 v[128:129], v[128:129], v[38:39] op_sel_hi:[1,0]
	v_pk_mul_f32 v[130:131], v[130:131], v[38:39] op_sel_hi:[1,0]
	v_pk_fma_f32 v[128:129], v[22:23], v[128:129], v[30:31]
	v_pk_fma_f32 v[130:131], v[24:25], v[130:131], v[32:33]
	v_cvt_pk_bf16_f32 v128, v128, v129
	v_cvt_pk_bf16_f32 v129, v130, v131
	global_store_dwordx2 v78, v[128:129], s[2:3] offset:1536
	s_add_u32 s0, s19, 7
	s_lshl_b32 s0, s0, 11
	s_add_u32 s2, s72, s0
	s_addc_u32 s3, s73, 0
	v_pk_mul_f32 v[132:133], v[132:133], v[40:41] op_sel_hi:[1,0]
	v_pk_mul_f32 v[134:135], v[134:135], v[40:41] op_sel_hi:[1,0]
	v_pk_fma_f32 v[132:133], v[2:3], v[132:133], v[10:11]
	v_pk_fma_f32 v[134:135], v[4:5], v[134:135], v[12:13]
	v_cvt_pk_bf16_f32 v132, v132, v133
	v_cvt_pk_bf16_f32 v133, v134, v135
	global_store_dwordx2 v78, v[132:133], s[2:3] offset:0
	v_pk_mul_f32 v[136:137], v[136:137], v[40:41] op_sel_hi:[1,0]
	v_pk_mul_f32 v[138:139], v[138:139], v[40:41] op_sel_hi:[1,0]
	v_pk_fma_f32 v[136:137], v[6:7], v[136:137], v[14:15]
	v_pk_fma_f32 v[138:139], v[8:9], v[138:139], v[16:17]
	v_cvt_pk_bf16_f32 v136, v136, v137
	v_cvt_pk_bf16_f32 v137, v138, v139
	global_store_dwordx2 v78, v[136:137], s[2:3] offset:512
	v_pk_mul_f32 v[140:141], v[140:141], v[40:41] op_sel_hi:[1,0]
	v_pk_mul_f32 v[142:143], v[142:143], v[40:41] op_sel_hi:[1,0]
	v_pk_fma_f32 v[140:141], v[18:19], v[140:141], v[26:27]
	v_pk_fma_f32 v[142:143], v[20:21], v[142:143], v[28:29]
	v_cvt_pk_bf16_f32 v140, v140, v141
	v_cvt_pk_bf16_f32 v141, v142, v143
	global_store_dwordx2 v78, v[140:141], s[2:3] offset:1024
	v_pk_mul_f32 v[144:145], v[144:145], v[40:41] op_sel_hi:[1,0]
	v_pk_mul_f32 v[146:147], v[146:147], v[40:41] op_sel_hi:[1,0]
	v_pk_fma_f32 v[144:145], v[22:23], v[144:145], v[30:31]
	v_pk_fma_f32 v[146:147], v[24:25], v[146:147], v[32:33]
	v_cvt_pk_bf16_f32 v144, v144, v145
	v_cvt_pk_bf16_f32 v145, v146, v147
	global_store_dwordx2 v78, v[144:145], s[2:3] offset:1536
	s_nop 1
	s_branch .LBB0_153

.Lp7n_nope_a0:
	v_lshlrev_b32_e32 v180, 16, v148
	v_and_b32_e32 v181, 0xffff0000, v148
	v_lshlrev_b32_e32 v182, 16, v149
	v_and_b32_e32 v183, 0xffff0000, v149
	v_lshlrev_b32_e32 v184, 16, v150
	v_and_b32_e32 v185, 0xffff0000, v150
	v_lshlrev_b32_e32 v186, 16, v151
	v_and_b32_e32 v187, 0xffff0000, v151
	v_lshlrev_b32_e32 v188, 16, v152
	v_and_b32_e32 v189, 0xffff0000, v152
	v_lshlrev_b32_e32 v190, 16, v153
	v_and_b32_e32 v191, 0xffff0000, v153
	v_lshlrev_b32_e32 v192, 16, v154
	v_and_b32_e32 v193, 0xffff0000, v154
	v_lshlrev_b32_e32 v194, 16, v155
	v_and_b32_e32 v195, 0xffff0000, v155
	v_lshlrev_b32_e32 v196, 16, v156
	v_and_b32_e32 v197, 0xffff0000, v156
	v_lshlrev_b32_e32 v198, 16, v157
	v_and_b32_e32 v199, 0xffff0000, v157
	v_lshlrev_b32_e32 v200, 16, v158
	v_and_b32_e32 v201, 0xffff0000, v158
	v_lshlrev_b32_e32 v202, 16, v159
	v_and_b32_e32 v203, 0xffff0000, v159
	v_lshlrev_b32_e32 v204, 16, v160
	v_and_b32_e32 v205, 0xffff0000, v160
	v_lshlrev_b32_e32 v206, 16, v161
	v_and_b32_e32 v207, 0xffff0000, v161
	v_lshlrev_b32_e32 v208, 16, v162
	v_and_b32_e32 v209, 0xffff0000, v162
	v_lshlrev_b32_e32 v210, 16, v163
	v_and_b32_e32 v211, 0xffff0000, v163
	v_lshlrev_b32_e32 v212, 16, v164
	v_and_b32_e32 v213, 0xffff0000, v164
	v_lshlrev_b32_e32 v214, 16, v165
	v_and_b32_e32 v215, 0xffff0000, v165
	v_lshlrev_b32_e32 v216, 16, v166
	v_and_b32_e32 v217, 0xffff0000, v166
	v_lshlrev_b32_e32 v218, 16, v167
	v_and_b32_e32 v219, 0xffff0000, v167
	v_lshlrev_b32_e32 v220, 16, v168
	v_and_b32_e32 v221, 0xffff0000, v168
	v_lshlrev_b32_e32 v222, 16, v169
	v_and_b32_e32 v223, 0xffff0000, v169
	v_lshlrev_b32_e32 v224, 16, v170
	v_and_b32_e32 v225, 0xffff0000, v170
	v_lshlrev_b32_e32 v226, 16, v171
	v_and_b32_e32 v227, 0xffff0000, v171
	v_lshlrev_b32_e32 v228, 16, v172
	v_and_b32_e32 v229, 0xffff0000, v172
	v_lshlrev_b32_e32 v230, 16, v173
	v_and_b32_e32 v231, 0xffff0000, v173
	v_lshlrev_b32_e32 v232, 16, v174
	v_and_b32_e32 v233, 0xffff0000, v174
	v_lshlrev_b32_e32 v234, 16, v175
	v_and_b32_e32 v235, 0xffff0000, v175
	v_lshlrev_b32_e32 v236, 16, v176
	v_and_b32_e32 v237, 0xffff0000, v176
	v_lshlrev_b32_e32 v238, 16, v177
	v_and_b32_e32 v239, 0xffff0000, v177
	v_lshlrev_b32_e32 v240, 16, v178
	v_and_b32_e32 v241, 0xffff0000, v178
	v_lshlrev_b32_e32 v242, 16, v179
	v_and_b32_e32 v243, 0xffff0000, v179
	v_pk_mul_f32 v[148:149], v[180:181], v[180:181]
	v_pk_mul_f32 v[156:157], v[196:197], v[196:197]
	v_pk_mul_f32 v[164:165], v[212:213], v[212:213]
	v_pk_mul_f32 v[172:173], v[228:229], v[228:229]
	v_pk_fma_f32 v[148:149], v[182:183], v[182:183], v[148:149]
	v_pk_fma_f32 v[156:157], v[198:199], v[198:199], v[156:157]
	v_pk_fma_f32 v[164:165], v[214:215], v[214:215], v[164:165]
	v_pk_fma_f32 v[172:173], v[230:231], v[230:231], v[172:173]
	v_pk_fma_f32 v[148:149], v[184:185], v[184:185], v[148:149]
	v_pk_fma_f32 v[156:157], v[200:201], v[200:201], v[156:157]
	v_pk_fma_f32 v[164:165], v[216:217], v[216:217], v[164:165]
	v_pk_fma_f32 v[172:173], v[232:233], v[232:233], v[172:173]
	v_pk_fma_f32 v[148:149], v[186:187], v[186:187], v[148:149]
	v_pk_fma_f32 v[156:157], v[202:203], v[202:203], v[156:157]
	v_pk_fma_f32 v[164:165], v[218:219], v[218:219], v[164:165]
	v_pk_fma_f32 v[172:173], v[234:235], v[234:235], v[172:173]
	v_pk_fma_f32 v[148:149], v[188:189], v[188:189], v[148:149]
	v_pk_fma_f32 v[156:157], v[204:205], v[204:205], v[156:157]
	v_pk_fma_f32 v[164:165], v[220:221], v[220:221], v[164:165]
	v_pk_fma_f32 v[172:173], v[236:237], v[236:237], v[172:173]
	v_pk_fma_f32 v[148:149], v[190:191], v[190:191], v[148:149]
	v_pk_fma_f32 v[156:157], v[206:207], v[206:207], v[156:157]
	v_pk_fma_f32 v[164:165], v[222:223], v[222:223], v[164:165]
	v_pk_fma_f32 v[172:173], v[238:239], v[238:239], v[172:173]
	v_pk_fma_f32 v[148:149], v[192:193], v[192:193], v[148:149]
	v_pk_fma_f32 v[156:157], v[208:209], v[208:209], v[156:157]
	v_pk_fma_f32 v[164:165], v[224:225], v[224:225], v[164:165]
	v_pk_fma_f32 v[172:173], v[240:241], v[240:241], v[172:173]
	v_pk_fma_f32 v[148:149], v[194:195], v[194:195], v[148:149]
	v_pk_fma_f32 v[156:157], v[210:211], v[210:211], v[156:157]
	v_pk_fma_f32 v[164:165], v[226:227], v[226:227], v[164:165]
	v_pk_fma_f32 v[172:173], v[242:243], v[242:243], v[172:173]
	v_add_f32_e32 v148, v148, v149
	v_add_f32_e32 v156, v156, v157
	v_add_f32_e32 v164, v164, v165
	v_add_f32_e32 v172, v172, v173
	v_add_f32_dpp v148, v148, v148 quad_perm:[1,0,3,2] row_mask:0xf bank_mask:0xf
	v_add_f32_dpp v156, v156, v156 quad_perm:[1,0,3,2] row_mask:0xf bank_mask:0xf
	v_add_f32_dpp v164, v164, v164 quad_perm:[1,0,3,2] row_mask:0xf bank_mask:0xf
	v_add_f32_dpp v172, v172, v172 quad_perm:[1,0,3,2] row_mask:0xf bank_mask:0xf
	v_add_f32_dpp v148, v148, v148 quad_perm:[2,3,0,1] row_mask:0xf bank_mask:0xf
	v_add_f32_dpp v156, v156, v156 quad_perm:[2,3,0,1] row_mask:0xf bank_mask:0xf
	v_add_f32_dpp v164, v164, v164 quad_perm:[2,3,0,1] row_mask:0xf bank_mask:0xf
	v_add_f32_dpp v172, v172, v172 quad_perm:[2,3,0,1] row_mask:0xf bank_mask:0xf
	v_add_f32_dpp v148, v148, v148 row_ror:4 row_mask:0xf bank_mask:0xf
	v_add_f32_dpp v156, v156, v156 row_ror:4 row_mask:0xf bank_mask:0xf
	v_add_f32_dpp v164, v164, v164 row_ror:4 row_mask:0xf bank_mask:0xf
	v_add_f32_dpp v172, v172, v172 row_ror:4 row_mask:0xf bank_mask:0xf
	v_add_f32_dpp v148, v148, v148 row_ror:8 row_mask:0xf bank_mask:0xf
	v_add_f32_dpp v156, v156, v156 row_ror:8 row_mask:0xf bank_mask:0xf
	v_add_f32_dpp v164, v164, v164 row_ror:8 row_mask:0xf bank_mask:0xf
	v_add_f32_dpp v172, v172, v172 row_ror:8 row_mask:0xf bank_mask:0xf
	ds_bpermute_b32 v149, v73, v148
	ds_bpermute_b32 v157, v73, v156
	ds_bpermute_b32 v165, v73, v164
	ds_bpermute_b32 v173, v73, v172
	s_waitcnt lgkmcnt(0)
	v_add_f32_e32 v148, v148, v149
	v_add_f32_e32 v156, v156, v157
	v_add_f32_e32 v164, v164, v165
	v_add_f32_e32 v172, v172, v173
	ds_bpermute_b32 v149, v74, v148
	ds_bpermute_b32 v157, v74, v156
	ds_bpermute_b32 v165, v74, v164
	ds_bpermute_b32 v173, v74, v172
	s_waitcnt lgkmcnt(0)
	v_add_f32_e32 v148, v148, v149
	v_add_f32_e32 v156, v156, v157
	v_add_f32_e32 v164, v164, v165
	v_add_f32_e32 v172, v172, v173
	v_fmamk_f32 v148, v148, 0x3a800000, v77
	v_fmamk_f32 v156, v156, 0x3a800000, v77
	v_fmamk_f32 v164, v164, 0x3a800000, v77
	v_fmamk_f32 v172, v172, 0x3a800000, v77
	v_mul_f32_e32 v150, 0x4b800000, v148
	v_cmp_gt_f32_e32 vcc, s26, v148
	s_nop 1
	v_cndmask_b32_e32 v148, v148, v150, vcc
	v_rsq_f32_e32 v148, v148
	s_nop 0
	v_mul_f32_e32 v150, 0x45800000, v148
	v_cndmask_b32_e32 v148, v148, v150, vcc
	v_mul_f32_e32 v158, 0x4b800000, v156
	v_cmp_gt_f32_e32 vcc, s26, v156
	s_nop 1
	v_cndmask_b32_e32 v156, v156, v158, vcc
	v_rsq_f32_e32 v156, v156
	s_nop 0
	v_mul_f32_e32 v158, 0x45800000, v156
	v_cndmask_b32_e32 v156, v156, v158, vcc
	v_mul_f32_e32 v166, 0x4b800000, v164
	v_cmp_gt_f32_e32 vcc, s26, v164
	s_nop 1
	v_cndmask_b32_e32 v164, v164, v166, vcc
	v_rsq_f32_e32 v164, v164
	s_nop 0
	v_mul_f32_e32 v166, 0x45800000, v164
	v_cndmask_b32_e32 v164, v164, v166, vcc
	v_mul_f32_e32 v174, 0x4b800000, v172
	v_cmp_gt_f32_e32 vcc, s26, v172
	s_nop 1
	v_cndmask_b32_e32 v172, v172, v174, vcc
	v_rsq_f32_e32 v172, v172
	s_nop 0
	v_mul_f32_e32 v174, 0x45800000, v172
	v_cndmask_b32_e32 v172, v172, v174, vcc
	s_add_u32 s2, s21, 0
	s_lshl_b32 s2, s2, 12
	s_add_u32 s10, s72, s2
	s_addc_u32 s11, s73, 0
	v_pk_mul_f32 v[180:181], v[180:181], v[148:149] op_sel_hi:[1,0]
	v_pk_mul_f32 v[182:183], v[182:183], v[148:149] op_sel_hi:[1,0]
	v_pk_fma_f32 v[84:85], v[2:3], v[180:181], v[84:85]
	v_pk_fma_f32 v[86:87], v[4:5], v[182:183], v[86:87]
	global_store_dwordx4 v79, v[84:87], s[10:11] offset:0 nt
	v_pk_mul_f32 v[184:185], v[184:185], v[148:149] op_sel_hi:[1,0]
	v_pk_mul_f32 v[186:187], v[186:187], v[148:149] op_sel_hi:[1,0]
	v_pk_fma_f32 v[88:89], v[6:7], v[184:185], v[88:89]
	v_pk_fma_f32 v[90:91], v[8:9], v[186:187], v[90:91]
	global_store_dwordx4 v79, v[88:91], s[10:11] offset:1024 nt
	v_pk_mul_f32 v[188:189], v[188:189], v[148:149] op_sel_hi:[1,0]
	v_pk_mul_f32 v[190:191], v[190:191], v[148:149] op_sel_hi:[1,0]
	v_pk_fma_f32 v[92:93], v[10:11], v[188:189], v[92:93]
	v_pk_fma_f32 v[94:95], v[12:13], v[190:191], v[94:95]
	global_store_dwordx4 v79, v[92:95], s[10:11] offset:2048 nt
	v_pk_mul_f32 v[192:193], v[192:193], v[148:149] op_sel_hi:[1,0]
	v_pk_mul_f32 v[194:195], v[194:195], v[148:149] op_sel_hi:[1,0]
	v_pk_fma_f32 v[96:97], v[14:15], v[192:193], v[96:97]
	v_pk_fma_f32 v[98:99], v[16:17], v[194:195], v[98:99]
	global_store_dwordx4 v79, v[96:99], s[10:11] offset:3072 nt
	s_add_u32 s2, s21, 1
	s_lshl_b32 s2, s2, 12
	s_add_u32 s10, s72, s2
	s_addc_u32 s11, s73, 0
	v_pk_mul_f32 v[196:197], v[196:197], v[156:157] op_sel_hi:[1,0]
	v_pk_mul_f32 v[198:199], v[198:199], v[156:157] op_sel_hi:[1,0]
	v_pk_fma_f32 v[100:101], v[2:3], v[196:197], v[100:101]
	v_pk_fma_f32 v[102:103], v[4:5], v[198:199], v[102:103]
	global_store_dwordx4 v79, v[100:103], s[10:11] offset:0 nt
	v_pk_mul_f32 v[200:201], v[200:201], v[156:157] op_sel_hi:[1,0]
	v_pk_mul_f32 v[202:203], v[202:203], v[156:157] op_sel_hi:[1,0]
	v_pk_fma_f32 v[104:105], v[6:7], v[200:201], v[104:105]
	v_pk_fma_f32 v[106:107], v[8:9], v[202:203], v[106:107]
	global_store_dwordx4 v79, v[104:107], s[10:11] offset:1024 nt
	v_pk_mul_f32 v[204:205], v[204:205], v[156:157] op_sel_hi:[1,0]
	v_pk_mul_f32 v[206:207], v[206:207], v[156:157] op_sel_hi:[1,0]
	v_pk_fma_f32 v[108:109], v[10:11], v[204:205], v[108:109]
	v_pk_fma_f32 v[110:111], v[12:13], v[206:207], v[110:111]
	global_store_dwordx4 v79, v[108:111], s[10:11] offset:2048 nt
	v_pk_mul_f32 v[208:209], v[208:209], v[156:157] op_sel_hi:[1,0]
	v_pk_mul_f32 v[210:211], v[210:211], v[156:157] op_sel_hi:[1,0]
	v_pk_fma_f32 v[112:113], v[14:15], v[208:209], v[112:113]
	v_pk_fma_f32 v[114:115], v[16:17], v[210:211], v[114:115]
	global_store_dwordx4 v79, v[112:115], s[10:11] offset:3072 nt
	s_add_u32 s2, s21, 2
	s_lshl_b32 s2, s2, 12
	s_add_u32 s10, s72, s2
	s_addc_u32 s11, s73, 0
	v_pk_mul_f32 v[212:213], v[212:213], v[164:165] op_sel_hi:[1,0]
	v_pk_mul_f32 v[214:215], v[214:215], v[164:165] op_sel_hi:[1,0]
	v_pk_fma_f32 v[116:117], v[2:3], v[212:213], v[116:117]
	v_pk_fma_f32 v[118:119], v[4:5], v[214:215], v[118:119]
	global_store_dwordx4 v79, v[116:119], s[10:11] offset:0 nt
	v_pk_mul_f32 v[216:217], v[216:217], v[164:165] op_sel_hi:[1,0]
	v_pk_mul_f32 v[218:219], v[218:219], v[164:165] op_sel_hi:[1,0]
	v_pk_fma_f32 v[120:121], v[6:7], v[216:217], v[120:121]
	v_pk_fma_f32 v[122:123], v[8:9], v[218:219], v[122:123]
	global_store_dwordx4 v79, v[120:123], s[10:11] offset:1024 nt
	v_pk_mul_f32 v[220:221], v[220:221], v[164:165] op_sel_hi:[1,0]
	v_pk_mul_f32 v[222:223], v[222:223], v[164:165] op_sel_hi:[1,0]
	v_pk_fma_f32 v[124:125], v[10:11], v[220:221], v[124:125]
	v_pk_fma_f32 v[126:127], v[12:13], v[222:223], v[126:127]
	global_store_dwordx4 v79, v[124:127], s[10:11] offset:2048 nt
	v_pk_mul_f32 v[224:225], v[224:225], v[164:165] op_sel_hi:[1,0]
	v_pk_mul_f32 v[226:227], v[226:227], v[164:165] op_sel_hi:[1,0]
	v_pk_fma_f32 v[128:129], v[14:15], v[224:225], v[128:129]
	v_pk_fma_f32 v[130:131], v[16:17], v[226:227], v[130:131]
	global_store_dwordx4 v79, v[128:131], s[10:11] offset:3072 nt
	s_add_u32 s2, s21, 3
	s_lshl_b32 s2, s2, 12
	s_add_u32 s10, s72, s2
	s_addc_u32 s11, s73, 0
	v_pk_mul_f32 v[228:229], v[228:229], v[172:173] op_sel_hi:[1,0]
	v_pk_mul_f32 v[230:231], v[230:231], v[172:173] op_sel_hi:[1,0]
	v_pk_fma_f32 v[132:133], v[2:3], v[228:229], v[132:133]
	v_pk_fma_f32 v[134:135], v[4:5], v[230:231], v[134:135]
	global_store_dwordx4 v79, v[132:135], s[10:11] offset:0 nt
	v_pk_mul_f32 v[232:233], v[232:233], v[172:173] op_sel_hi:[1,0]
	v_pk_mul_f32 v[234:235], v[234:235], v[172:173] op_sel_hi:[1,0]
	v_pk_fma_f32 v[136:137], v[6:7], v[232:233], v[136:137]
	v_pk_fma_f32 v[138:139], v[8:9], v[234:235], v[138:139]
	global_store_dwordx4 v79, v[136:139], s[10:11] offset:1024 nt
	v_pk_mul_f32 v[236:237], v[236:237], v[172:173] op_sel_hi:[1,0]
	v_pk_mul_f32 v[238:239], v[238:239], v[172:173] op_sel_hi:[1,0]
	v_pk_fma_f32 v[140:141], v[10:11], v[236:237], v[140:141]
	v_pk_fma_f32 v[142:143], v[12:13], v[238:239], v[142:143]
	global_store_dwordx4 v79, v[140:143], s[10:11] offset:2048 nt
	v_pk_mul_f32 v[240:241], v[240:241], v[172:173] op_sel_hi:[1,0]
	v_pk_mul_f32 v[242:243], v[242:243], v[172:173] op_sel_hi:[1,0]
	v_pk_fma_f32 v[144:145], v[14:15], v[240:241], v[144:145]
	v_pk_fma_f32 v[146:147], v[16:17], v[242:243], v[146:147]
	global_store_dwordx4 v79, v[144:147], s[10:11] offset:3072 nt
	s_nop 1
	s_add_u32 s2, s21, 4
	s_mul_i32 s12, s2, 0x3000
	s_add_u32 s10, s74, 0x39c4000
	s_addc_u32 s11, s75, 0
	s_add_u32 s10, s10, s12
	s_addc_u32 s11, s11, 0
	global_load_dwordx2 v[148:149], v80, s[10:11] offset:0 nt
	global_load_dwordx2 v[150:151], v80, s[10:11] offset:512 nt
	global_load_dwordx2 v[152:153], v80, s[10:11] offset:1024 nt
	global_load_dwordx2 v[154:155], v80, s[10:11] offset:1536 nt
	s_cmpk_lt_u32 s2, 0x2000
	s_cselect_b32 s10, s4, s6
	s_cselect_b32 s11, s5, s7
	s_and_b32 s12, s2, 0x1fff
	s_lshl_b32 s12, s12, 12
	s_add_u32 s10, s10, s12
	s_addc_u32 s11, s11, 0
	global_load_dwordx4 v[84:87], v79, s[10:11] offset:0 nt
	global_load_dwordx4 v[88:91], v79, s[10:11] offset:1024 nt
	global_load_dwordx4 v[92:95], v79, s[10:11] offset:2048 nt
	global_load_dwordx4 v[96:99], v79, s[10:11] offset:3072 nt
	s_cmp_eq_u32 s28, 0
	s_cbranch_scc1 .Lp7n_nocol_a4
	s_and_b32 s12, s2, 63
	s_lshl_b32 s12, s12, 10
	s_add_u32 s10, s74, 0x94000
	s_addc_u32 s11, s75, 0
	s_add_u32 s10, s10, s12
	s_addc_u32 s11, s11, 0
	global_load_dwordx4 v[18:21], v79, s[10:11]
	s_add_u32 s10, s10, 0x10000
	s_addc_u32 s11, s11, 0
	global_load_dwordx4 v[22:25], v79, s[10:11]

.Lp7n_nope_a1:
	v_lshlrev_b32_e32 v180, 16, v148
	v_and_b32_e32 v181, 0xffff0000, v148
	v_lshlrev_b32_e32 v182, 16, v149
	v_and_b32_e32 v183, 0xffff0000, v149
	v_lshlrev_b32_e32 v184, 16, v150
	v_and_b32_e32 v185, 0xffff0000, v150
	v_lshlrev_b32_e32 v186, 16, v151
	v_and_b32_e32 v187, 0xffff0000, v151
	v_lshlrev_b32_e32 v188, 16, v152
	v_and_b32_e32 v189, 0xffff0000, v152
	v_lshlrev_b32_e32 v190, 16, v153
	v_and_b32_e32 v191, 0xffff0000, v153
	v_lshlrev_b32_e32 v192, 16, v154
	v_and_b32_e32 v193, 0xffff0000, v154
	v_lshlrev_b32_e32 v194, 16, v155
	v_and_b32_e32 v195, 0xffff0000, v155
	v_lshlrev_b32_e32 v196, 16, v156
	v_and_b32_e32 v197, 0xffff0000, v156
	v_lshlrev_b32_e32 v198, 16, v157
	v_and_b32_e32 v199, 0xffff0000, v157
	v_lshlrev_b32_e32 v200, 16, v158
	v_and_b32_e32 v201, 0xffff0000, v158
	v_lshlrev_b32_e32 v202, 16, v159
	v_and_b32_e32 v203, 0xffff0000, v159
	v_lshlrev_b32_e32 v204, 16, v160
	v_and_b32_e32 v205, 0xffff0000, v160
	v_lshlrev_b32_e32 v206, 16, v161
	v_and_b32_e32 v207, 0xffff0000, v161
	v_lshlrev_b32_e32 v208, 16, v162
	v_and_b32_e32 v209, 0xffff0000, v162
	v_lshlrev_b32_e32 v210, 16, v163
	v_and_b32_e32 v211, 0xffff0000, v163
	v_lshlrev_b32_e32 v212, 16, v164
	v_and_b32_e32 v213, 0xffff0000, v164
	v_lshlrev_b32_e32 v214, 16, v165
	v_and_b32_e32 v215, 0xffff0000, v165
	v_lshlrev_b32_e32 v216, 16, v166
	v_and_b32_e32 v217, 0xffff0000, v166
	v_lshlrev_b32_e32 v218, 16, v167
	v_and_b32_e32 v219, 0xffff0000, v167
	v_lshlrev_b32_e32 v220, 16, v168
	v_and_b32_e32 v221, 0xffff0000, v168
	v_lshlrev_b32_e32 v222, 16, v169
	v_and_b32_e32 v223, 0xffff0000, v169
	v_lshlrev_b32_e32 v224, 16, v170
	v_and_b32_e32 v225, 0xffff0000, v170
	v_lshlrev_b32_e32 v226, 16, v171
	v_and_b32_e32 v227, 0xffff0000, v171
	v_lshlrev_b32_e32 v228, 16, v172
	v_and_b32_e32 v229, 0xffff0000, v172
	v_lshlrev_b32_e32 v230, 16, v173
	v_and_b32_e32 v231, 0xffff0000, v173
	v_lshlrev_b32_e32 v232, 16, v174
	v_and_b32_e32 v233, 0xffff0000, v174
	v_lshlrev_b32_e32 v234, 16, v175
	v_and_b32_e32 v235, 0xffff0000, v175
	v_lshlrev_b32_e32 v236, 16, v176
	v_and_b32_e32 v237, 0xffff0000, v176
	v_lshlrev_b32_e32 v238, 16, v177
	v_and_b32_e32 v239, 0xffff0000, v177
	v_lshlrev_b32_e32 v240, 16, v178
	v_and_b32_e32 v241, 0xffff0000, v178
	v_lshlrev_b32_e32 v242, 16, v179
	v_and_b32_e32 v243, 0xffff0000, v179
	v_pk_mul_f32 v[148:149], v[180:181], v[180:181]
	v_pk_mul_f32 v[156:157], v[196:197], v[196:197]
	v_pk_mul_f32 v[164:165], v[212:213], v[212:213]
	v_pk_mul_f32 v[172:173], v[228:229], v[228:229]
	v_pk_fma_f32 v[148:149], v[182:183], v[182:183], v[148:149]
	v_pk_fma_f32 v[156:157], v[198:199], v[198:199], v[156:157]
	v_pk_fma_f32 v[164:165], v[214:215], v[214:215], v[164:165]
	v_pk_fma_f32 v[172:173], v[230:231], v[230:231], v[172:173]
	v_pk_fma_f32 v[148:149], v[184:185], v[184:185], v[148:149]
	v_pk_fma_f32 v[156:157], v[200:201], v[200:201], v[156:157]
	v_pk_fma_f32 v[164:165], v[216:217], v[216:217], v[164:165]
	v_pk_fma_f32 v[172:173], v[232:233], v[232:233], v[172:173]
	v_pk_fma_f32 v[148:149], v[186:187], v[186:187], v[148:149]
	v_pk_fma_f32 v[156:157], v[202:203], v[202:203], v[156:157]
	v_pk_fma_f32 v[164:165], v[218:219], v[218:219], v[164:165]
	v_pk_fma_f32 v[172:173], v[234:235], v[234:235], v[172:173]
	v_pk_fma_f32 v[148:149], v[188:189], v[188:189], v[148:149]
	v_pk_fma_f32 v[156:157], v[204:205], v[204:205], v[156:157]
	v_pk_fma_f32 v[164:165], v[220:221], v[220:221], v[164:165]
	v_pk_fma_f32 v[172:173], v[236:237], v[236:237], v[172:173]
	v_pk_fma_f32 v[148:149], v[190:191], v[190:191], v[148:149]
	v_pk_fma_f32 v[156:157], v[206:207], v[206:207], v[156:157]
	v_pk_fma_f32 v[164:165], v[222:223], v[222:223], v[164:165]
	v_pk_fma_f32 v[172:173], v[238:239], v[238:239], v[172:173]
	v_pk_fma_f32 v[148:149], v[192:193], v[192:193], v[148:149]
	v_pk_fma_f32 v[156:157], v[208:209], v[208:209], v[156:157]
	v_pk_fma_f32 v[164:165], v[224:225], v[224:225], v[164:165]
	v_pk_fma_f32 v[172:173], v[240:241], v[240:241], v[172:173]
	v_pk_fma_f32 v[148:149], v[194:195], v[194:195], v[148:149]
	v_pk_fma_f32 v[156:157], v[210:211], v[210:211], v[156:157]
	v_pk_fma_f32 v[164:165], v[226:227], v[226:227], v[164:165]
	v_pk_fma_f32 v[172:173], v[242:243], v[242:243], v[172:173]
	v_add_f32_e32 v148, v148, v149
	v_add_f32_e32 v156, v156, v157
	v_add_f32_e32 v164, v164, v165
	v_add_f32_e32 v172, v172, v173
	v_add_f32_dpp v148, v148, v148 quad_perm:[1,0,3,2] row_mask:0xf bank_mask:0xf
	v_add_f32_dpp v156, v156, v156 quad_perm:[1,0,3,2] row_mask:0xf bank_mask:0xf
	v_add_f32_dpp v164, v164, v164 quad_perm:[1,0,3,2] row_mask:0xf bank_mask:0xf
	v_add_f32_dpp v172, v172, v172 quad_perm:[1,0,3,2] row_mask:0xf bank_mask:0xf
	v_add_f32_dpp v148, v148, v148 quad_perm:[2,3,0,1] row_mask:0xf bank_mask:0xf
	v_add_f32_dpp v156, v156, v156 quad_perm:[2,3,0,1] row_mask:0xf bank_mask:0xf
	v_add_f32_dpp v164, v164, v164 quad_perm:[2,3,0,1] row_mask:0xf bank_mask:0xf
	v_add_f32_dpp v172, v172, v172 quad_perm:[2,3,0,1] row_mask:0xf bank_mask:0xf
	v_add_f32_dpp v148, v148, v148 row_ror:4 row_mask:0xf bank_mask:0xf
	v_add_f32_dpp v156, v156, v156 row_ror:4 row_mask:0xf bank_mask:0xf
	v_add_f32_dpp v164, v164, v164 row_ror:4 row_mask:0xf bank_mask:0xf
	v_add_f32_dpp v172, v172, v172 row_ror:4 row_mask:0xf bank_mask:0xf
	v_add_f32_dpp v148, v148, v148 row_ror:8 row_mask:0xf bank_mask:0xf
	v_add_f32_dpp v156, v156, v156 row_ror:8 row_mask:0xf bank_mask:0xf
	v_add_f32_dpp v164, v164, v164 row_ror:8 row_mask:0xf bank_mask:0xf
	v_add_f32_dpp v172, v172, v172 row_ror:8 row_mask:0xf bank_mask:0xf
	ds_bpermute_b32 v149, v73, v148
	ds_bpermute_b32 v157, v73, v156
	ds_bpermute_b32 v165, v73, v164
	ds_bpermute_b32 v173, v73, v172
	s_waitcnt lgkmcnt(0)
	v_add_f32_e32 v148, v148, v149
	v_add_f32_e32 v156, v156, v157
	v_add_f32_e32 v164, v164, v165
	v_add_f32_e32 v172, v172, v173
	ds_bpermute_b32 v149, v74, v148
	ds_bpermute_b32 v157, v74, v156
	ds_bpermute_b32 v165, v74, v164
	ds_bpermute_b32 v173, v74, v172
	s_waitcnt lgkmcnt(0)
	v_add_f32_e32 v148, v148, v149
	v_add_f32_e32 v156, v156, v157
	v_add_f32_e32 v164, v164, v165
	v_add_f32_e32 v172, v172, v173
	v_fmamk_f32 v148, v148, 0x3a800000, v77
	v_fmamk_f32 v156, v156, 0x3a800000, v77
	v_fmamk_f32 v164, v164, 0x3a800000, v77
	v_fmamk_f32 v172, v172, 0x3a800000, v77
	v_mul_f32_e32 v150, 0x4b800000, v148
	v_cmp_gt_f32_e32 vcc, s26, v148
	s_nop 1
	v_cndmask_b32_e32 v148, v148, v150, vcc
	v_rsq_f32_e32 v148, v148
	s_nop 0
	v_mul_f32_e32 v150, 0x45800000, v148
	v_cndmask_b32_e32 v148, v148, v150, vcc
	v_mul_f32_e32 v158, 0x4b800000, v156
	v_cmp_gt_f32_e32 vcc, s26, v156
	s_nop 1
	v_cndmask_b32_e32 v156, v156, v158, vcc
	v_rsq_f32_e32 v156, v156
	s_nop 0
	v_mul_f32_e32 v158, 0x45800000, v156
	v_cndmask_b32_e32 v156, v156, v158, vcc
	v_mul_f32_e32 v166, 0x4b800000, v164
	v_cmp_gt_f32_e32 vcc, s26, v164
	s_nop 1
	v_cndmask_b32_e32 v164, v164, v166, vcc
	v_rsq_f32_e32 v164, v164
	s_nop 0
	v_mul_f32_e32 v166, 0x45800000, v164
	v_cndmask_b32_e32 v164, v164, v166, vcc
	v_mul_f32_e32 v174, 0x4b800000, v172
	v_cmp_gt_f32_e32 vcc, s26, v172
	s_nop 1
	v_cndmask_b32_e32 v172, v172, v174, vcc
	v_rsq_f32_e32 v172, v172
	s_nop 0
	v_mul_f32_e32 v174, 0x45800000, v172
	v_cndmask_b32_e32 v172, v172, v174, vcc
	s_add_u32 s2, s21, 4
	s_lshl_b32 s2, s2, 12
	s_add_u32 s10, s72, s2
	s_addc_u32 s11, s73, 0
	v_pk_mul_f32 v[180:181], v[180:181], v[148:149] op_sel_hi:[1,0]
	v_pk_mul_f32 v[182:183], v[182:183], v[148:149] op_sel_hi:[1,0]
	v_pk_fma_f32 v[84:85], v[2:3], v[180:181], v[84:85]
	v_pk_fma_f32 v[86:87], v[4:5], v[182:183], v[86:87]
	global_store_dwordx4 v79, v[84:87], s[10:11] offset:0 nt
	v_pk_mul_f32 v[184:185], v[184:185], v[148:149] op_sel_hi:[1,0]
	v_pk_mul_f32 v[186:187], v[186:187], v[148:149] op_sel_hi:[1,0]
	v_pk_fma_f32 v[88:89], v[6:7], v[184:185], v[88:89]
	v_pk_fma_f32 v[90:91], v[8:9], v[186:187], v[90:91]
	global_store_dwordx4 v79, v[88:91], s[10:11] offset:1024 nt
	v_pk_mul_f32 v[188:189], v[188:189], v[148:149] op_sel_hi:[1,0]
	v_pk_mul_f32 v[190:191], v[190:191], v[148:149] op_sel_hi:[1,0]
	v_pk_fma_f32 v[92:93], v[10:11], v[188:189], v[92:93]
	v_pk_fma_f32 v[94:95], v[12:13], v[190:191], v[94:95]
	global_store_dwordx4 v79, v[92:95], s[10:11] offset:2048 nt
	v_pk_mul_f32 v[192:193], v[192:193], v[148:149] op_sel_hi:[1,0]
	v_pk_mul_f32 v[194:195], v[194:195], v[148:149] op_sel_hi:[1,0]
	v_pk_fma_f32 v[96:97], v[14:15], v[192:193], v[96:97]
	v_pk_fma_f32 v[98:99], v[16:17], v[194:195], v[98:99]
	global_store_dwordx4 v79, v[96:99], s[10:11] offset:3072 nt
	s_add_u32 s2, s21, 5
	s_lshl_b32 s2, s2, 12
	s_add_u32 s10, s72, s2
	s_addc_u32 s11, s73, 0
	v_pk_mul_f32 v[196:197], v[196:197], v[156:157] op_sel_hi:[1,0]
	v_pk_mul_f32 v[198:199], v[198:199], v[156:157] op_sel_hi:[1,0]
	v_pk_fma_f32 v[100:101], v[2:3], v[196:197], v[100:101]
	v_pk_fma_f32 v[102:103], v[4:5], v[198:199], v[102:103]
	global_store_dwordx4 v79, v[100:103], s[10:11] offset:0 nt
	v_pk_mul_f32 v[200:201], v[200:201], v[156:157] op_sel_hi:[1,0]
	v_pk_mul_f32 v[202:203], v[202:203], v[156:157] op_sel_hi:[1,0]
	v_pk_fma_f32 v[104:105], v[6:7], v[200:201], v[104:105]
	v_pk_fma_f32 v[106:107], v[8:9], v[202:203], v[106:107]
	global_store_dwordx4 v79, v[104:107], s[10:11] offset:1024 nt
	v_pk_mul_f32 v[204:205], v[204:205], v[156:157] op_sel_hi:[1,0]
	v_pk_mul_f32 v[206:207], v[206:207], v[156:157] op_sel_hi:[1,0]
	v_pk_fma_f32 v[108:109], v[10:11], v[204:205], v[108:109]
	v_pk_fma_f32 v[110:111], v[12:13], v[206:207], v[110:111]
	global_store_dwordx4 v79, v[108:111], s[10:11] offset:2048 nt
	v_pk_mul_f32 v[208:209], v[208:209], v[156:157] op_sel_hi:[1,0]
	v_pk_mul_f32 v[210:211], v[210:211], v[156:157] op_sel_hi:[1,0]
	v_pk_fma_f32 v[112:113], v[14:15], v[208:209], v[112:113]
	v_pk_fma_f32 v[114:115], v[16:17], v[210:211], v[114:115]
	global_store_dwordx4 v79, v[112:115], s[10:11] offset:3072 nt
	s_add_u32 s2, s21, 6
	s_lshl_b32 s2, s2, 12
	s_add_u32 s10, s72, s2
	s_addc_u32 s11, s73, 0
	v_pk_mul_f32 v[212:213], v[212:213], v[164:165] op_sel_hi:[1,0]
	v_pk_mul_f32 v[214:215], v[214:215], v[164:165] op_sel_hi:[1,0]
	v_pk_fma_f32 v[116:117], v[2:3], v[212:213], v[116:117]
	v_pk_fma_f32 v[118:119], v[4:5], v[214:215], v[118:119]
	global_store_dwordx4 v79, v[116:119], s[10:11] offset:0 nt
	v_pk_mul_f32 v[216:217], v[216:217], v[164:165] op_sel_hi:[1,0]
	v_pk_mul_f32 v[218:219], v[218:219], v[164:165] op_sel_hi:[1,0]
	v_pk_fma_f32 v[120:121], v[6:7], v[216:217], v[120:121]
	v_pk_fma_f32 v[122:123], v[8:9], v[218:219], v[122:123]
	global_store_dwordx4 v79, v[120:123], s[10:11] offset:1024 nt
	v_pk_mul_f32 v[220:221], v[220:221], v[164:165] op_sel_hi:[1,0]
	v_pk_mul_f32 v[222:223], v[222:223], v[164:165] op_sel_hi:[1,0]
	v_pk_fma_f32 v[124:125], v[10:11], v[220:221], v[124:125]
	v_pk_fma_f32 v[126:127], v[12:13], v[222:223], v[126:127]
	global_store_dwordx4 v79, v[124:127], s[10:11] offset:2048 nt
	v_pk_mul_f32 v[224:225], v[224:225], v[164:165] op_sel_hi:[1,0]
	v_pk_mul_f32 v[226:227], v[226:227], v[164:165] op_sel_hi:[1,0]
	v_pk_fma_f32 v[128:129], v[14:15], v[224:225], v[128:129]
	v_pk_fma_f32 v[130:131], v[16:17], v[226:227], v[130:131]
	global_store_dwordx4 v79, v[128:131], s[10:11] offset:3072 nt
	s_add_u32 s2, s21, 7
	s_lshl_b32 s2, s2, 12
	s_add_u32 s10, s72, s2
	s_addc_u32 s11, s73, 0
	v_pk_mul_f32 v[228:229], v[228:229], v[172:173] op_sel_hi:[1,0]
	v_pk_mul_f32 v[230:231], v[230:231], v[172:173] op_sel_hi:[1,0]
	v_pk_fma_f32 v[132:133], v[2:3], v[228:229], v[132:133]
	v_pk_fma_f32 v[134:135], v[4:5], v[230:231], v[134:135]
	global_store_dwordx4 v79, v[132:135], s[10:11] offset:0 nt
	v_pk_mul_f32 v[232:233], v[232:233], v[172:173] op_sel_hi:[1,0]
	v_pk_mul_f32 v[234:235], v[234:235], v[172:173] op_sel_hi:[1,0]
	v_pk_fma_f32 v[136:137], v[6:7], v[232:233], v[136:137]
	v_pk_fma_f32 v[138:139], v[8:9], v[234:235], v[138:139]
	global_store_dwordx4 v79, v[136:139], s[10:11] offset:1024 nt
	v_pk_mul_f32 v[236:237], v[236:237], v[172:173] op_sel_hi:[1,0]
	v_pk_mul_f32 v[238:239], v[238:239], v[172:173] op_sel_hi:[1,0]
	v_pk_fma_f32 v[140:141], v[10:11], v[236:237], v[140:141]
	v_pk_fma_f32 v[142:143], v[12:13], v[238:239], v[142:143]
	global_store_dwordx4 v79, v[140:143], s[10:11] offset:2048 nt
	v_pk_mul_f32 v[240:241], v[240:241], v[172:173] op_sel_hi:[1,0]
	v_pk_mul_f32 v[242:243], v[242:243], v[172:173] op_sel_hi:[1,0]
	v_pk_fma_f32 v[144:145], v[14:15], v[240:241], v[144:145]
	v_pk_fma_f32 v[146:147], v[16:17], v[242:243], v[146:147]
	global_store_dwordx4 v79, v[144:147], s[10:11] offset:3072 nt
	s_nop 1
	s_branch .LBB0_1002

.Lp7n_nope_b0:
	v_lshlrev_b32_e32 v180, 16, v148
	v_and_b32_e32 v181, 0xffff0000, v148
	v_lshlrev_b32_e32 v182, 16, v149
	v_and_b32_e32 v183, 0xffff0000, v149
	v_lshlrev_b32_e32 v184, 16, v150
	v_and_b32_e32 v185, 0xffff0000, v150
	v_lshlrev_b32_e32 v186, 16, v151
	v_and_b32_e32 v187, 0xffff0000, v151
	v_lshlrev_b32_e32 v188, 16, v152
	v_and_b32_e32 v189, 0xffff0000, v152
	v_lshlrev_b32_e32 v190, 16, v153
	v_and_b32_e32 v191, 0xffff0000, v153
	v_lshlrev_b32_e32 v192, 16, v154
	v_and_b32_e32 v193, 0xffff0000, v154
	v_lshlrev_b32_e32 v194, 16, v155
	v_and_b32_e32 v195, 0xffff0000, v155
	v_lshlrev_b32_e32 v196, 16, v156
	v_and_b32_e32 v197, 0xffff0000, v156
	v_lshlrev_b32_e32 v198, 16, v157
	v_and_b32_e32 v199, 0xffff0000, v157
	v_lshlrev_b32_e32 v200, 16, v158
	v_and_b32_e32 v201, 0xffff0000, v158
	v_lshlrev_b32_e32 v202, 16, v159
	v_and_b32_e32 v203, 0xffff0000, v159
	v_lshlrev_b32_e32 v204, 16, v160
	v_and_b32_e32 v205, 0xffff0000, v160
	v_lshlrev_b32_e32 v206, 16, v161
	v_and_b32_e32 v207, 0xffff0000, v161
	v_lshlrev_b32_e32 v208, 16, v162
	v_and_b32_e32 v209, 0xffff0000, v162
	v_lshlrev_b32_e32 v210, 16, v163
	v_and_b32_e32 v211, 0xffff0000, v163
	v_pk_mul_f32 v[148:149], v[180:181], v[180:181]
	v_pk_mul_f32 v[156:157], v[196:197], v[196:197]
	v_pk_fma_f32 v[148:149], v[182:183], v[182:183], v[148:149]
	v_pk_fma_f32 v[156:157], v[198:199], v[198:199], v[156:157]
	v_pk_fma_f32 v[148:149], v[184:185], v[184:185], v[148:149]
	v_pk_fma_f32 v[156:157], v[200:201], v[200:201], v[156:157]
	v_pk_fma_f32 v[148:149], v[186:187], v[186:187], v[148:149]
	v_pk_fma_f32 v[156:157], v[202:203], v[202:203], v[156:157]
	v_pk_fma_f32 v[148:149], v[188:189], v[188:189], v[148:149]
	v_pk_fma_f32 v[156:157], v[204:205], v[204:205], v[156:157]
	v_pk_fma_f32 v[148:149], v[190:191], v[190:191], v[148:149]
	v_pk_fma_f32 v[156:157], v[206:207], v[206:207], v[156:157]
	v_pk_fma_f32 v[148:149], v[192:193], v[192:193], v[148:149]
	v_pk_fma_f32 v[156:157], v[208:209], v[208:209], v[156:157]
	v_pk_fma_f32 v[148:149], v[194:195], v[194:195], v[148:149]
	v_pk_fma_f32 v[156:157], v[210:211], v[210:211], v[156:157]
	v_add_f32_e32 v148, v148, v149
	v_add_f32_e32 v156, v156, v157
	s_nop 0
	v_add_f32_dpp v148, v148, v148 quad_perm:[1,0,3,2] row_mask:0xf bank_mask:0xf
	v_add_f32_dpp v156, v156, v156 quad_perm:[1,0,3,2] row_mask:0xf bank_mask:0xf
	s_nop 0
	v_add_f32_dpp v148, v148, v148 quad_perm:[2,3,0,1] row_mask:0xf bank_mask:0xf
	v_add_f32_dpp v156, v156, v156 quad_perm:[2,3,0,1] row_mask:0xf bank_mask:0xf
	s_nop 0
	v_add_f32_dpp v148, v148, v148 row_ror:4 row_mask:0xf bank_mask:0xf
	v_add_f32_dpp v156, v156, v156 row_ror:4 row_mask:0xf bank_mask:0xf
	s_nop 0
	v_add_f32_dpp v148, v148, v148 row_ror:8 row_mask:0xf bank_mask:0xf
	v_add_f32_dpp v156, v156, v156 row_ror:8 row_mask:0xf bank_mask:0xf
	s_nop 0
	ds_bpermute_b32 v149, v73, v148
	ds_bpermute_b32 v157, v73, v156
	s_waitcnt lgkmcnt(0)
	v_add_f32_e32 v148, v148, v149
	v_add_f32_e32 v156, v156, v157
	ds_bpermute_b32 v149, v74, v148
	ds_bpermute_b32 v157, v74, v156
	s_waitcnt lgkmcnt(0)
	v_add_f32_e32 v148, v148, v149
	v_add_f32_e32 v156, v156, v157
	v_fmamk_f32 v148, v148, 0x3a800000, v77
	v_fmamk_f32 v156, v156, 0x3a800000, v77
	v_mul_f32_e32 v150, 0x4b800000, v148
	v_cmp_gt_f32_e32 vcc, s26, v148
	s_nop 1
	v_cndmask_b32_e32 v148, v148, v150, vcc
	v_rsq_f32_e32 v148, v148
	s_nop 0
	v_mul_f32_e32 v150, 0x45800000, v148
	v_cndmask_b32_e32 v148, v148, v150, vcc
	v_mul_f32_e32 v158, 0x4b800000, v156
	v_cmp_gt_f32_e32 vcc, s26, v156
	s_nop 1
	v_cndmask_b32_e32 v156, v156, v158, vcc
	v_rsq_f32_e32 v156, v156
	s_nop 0
	v_mul_f32_e32 v158, 0x45800000, v156
	v_cndmask_b32_e32 v156, v156, v158, vcc
	s_add_u32 s2, s21, 0
	s_lshl_b32 s2, s2, 12
	s_add_u32 s10, s72, s2
	s_addc_u32 s11, s73, 0
	v_pk_mul_f32 v[180:181], v[180:181], v[148:149] op_sel_hi:[1,0]
	v_pk_mul_f32 v[182:183], v[182:183], v[148:149] op_sel_hi:[1,0]
	v_pk_fma_f32 v[84:85], v[2:3], v[180:181], v[84:85]
	v_pk_fma_f32 v[86:87], v[4:5], v[182:183], v[86:87]
	global_store_dwordx4 v79, v[84:87], s[10:11] offset:0 nt
	v_pk_mul_f32 v[184:185], v[184:185], v[148:149] op_sel_hi:[1,0]
	v_pk_mul_f32 v[186:187], v[186:187], v[148:149] op_sel_hi:[1,0]
	v_pk_fma_f32 v[88:89], v[6:7], v[184:185], v[88:89]
	v_pk_fma_f32 v[90:91], v[8:9], v[186:187], v[90:91]
	global_store_dwordx4 v79, v[88:91], s[10:11] offset:1024 nt
	v_pk_mul_f32 v[188:189], v[188:189], v[148:149] op_sel_hi:[1,0]
	v_pk_mul_f32 v[190:191], v[190:191], v[148:149] op_sel_hi:[1,0]
	v_pk_fma_f32 v[92:93], v[10:11], v[188:189], v[92:93]
	v_pk_fma_f32 v[94:95], v[12:13], v[190:191], v[94:95]
	global_store_dwordx4 v79, v[92:95], s[10:11] offset:2048 nt
	v_pk_mul_f32 v[192:193], v[192:193], v[148:149] op_sel_hi:[1,0]
	v_pk_mul_f32 v[194:195], v[194:195], v[148:149] op_sel_hi:[1,0]
	v_pk_fma_f32 v[96:97], v[14:15], v[192:193], v[96:97]
	v_pk_fma_f32 v[98:99], v[16:17], v[194:195], v[98:99]
	global_store_dwordx4 v79, v[96:99], s[10:11] offset:3072 nt
	s_add_u32 s2, s21, 1
	s_lshl_b32 s2, s2, 12
	s_add_u32 s10, s72, s2
	s_addc_u32 s11, s73, 0
	v_pk_mul_f32 v[196:197], v[196:197], v[156:157] op_sel_hi:[1,0]
	v_pk_mul_f32 v[198:199], v[198:199], v[156:157] op_sel_hi:[1,0]
	v_pk_fma_f32 v[100:101], v[2:3], v[196:197], v[100:101]
	v_pk_fma_f32 v[102:103], v[4:5], v[198:199], v[102:103]
	global_store_dwordx4 v79, v[100:103], s[10:11] offset:0 nt
	v_pk_mul_f32 v[200:201], v[200:201], v[156:157] op_sel_hi:[1,0]
	v_pk_mul_f32 v[202:203], v[202:203], v[156:157] op_sel_hi:[1,0]
	v_pk_fma_f32 v[104:105], v[6:7], v[200:201], v[104:105]
	v_pk_fma_f32 v[106:107], v[8:9], v[202:203], v[106:107]
	global_store_dwordx4 v79, v[104:107], s[10:11] offset:1024 nt
	v_pk_mul_f32 v[204:205], v[204:205], v[156:157] op_sel_hi:[1,0]
	v_pk_mul_f32 v[206:207], v[206:207], v[156:157] op_sel_hi:[1,0]
	v_pk_fma_f32 v[108:109], v[10:11], v[204:205], v[108:109]
	v_pk_fma_f32 v[110:111], v[12:13], v[206:207], v[110:111]
	global_store_dwordx4 v79, v[108:111], s[10:11] offset:2048 nt
	v_pk_mul_f32 v[208:209], v[208:209], v[156:157] op_sel_hi:[1,0]
	v_pk_mul_f32 v[210:211], v[210:211], v[156:157] op_sel_hi:[1,0]
	v_pk_fma_f32 v[112:113], v[14:15], v[208:209], v[112:113]
	v_pk_fma_f32 v[114:115], v[16:17], v[210:211], v[114:115]
	global_store_dwordx4 v79, v[112:115], s[10:11] offset:3072 nt
	s_nop 1
	s_add_u32 s2, s21, 2
	s_mul_i32 s12, s2, 0x3000
	s_add_u32 s10, s74, 0x39c4000
	s_addc_u32 s11, s75, 0
	s_add_u32 s10, s10, s12
	s_addc_u32 s11, s11, 0
	global_load_dwordx2 v[148:149], v80, s[10:11] offset:0 nt
	global_load_dwordx2 v[150:151], v80, s[10:11] offset:512 nt
	global_load_dwordx2 v[152:153], v80, s[10:11] offset:1024 nt
	global_load_dwordx2 v[154:155], v80, s[10:11] offset:1536 nt
	s_cmpk_lt_u32 s2, 0x2000
	s_cselect_b32 s10, s4, s6
	s_cselect_b32 s11, s5, s7
	s_and_b32 s12, s2, 0x1fff
	s_lshl_b32 s12, s12, 12
	s_add_u32 s10, s10, s12
	s_addc_u32 s11, s11, 0
	global_load_dwordx4 v[84:87], v79, s[10:11] offset:0 nt
	global_load_dwordx4 v[88:91], v79, s[10:11] offset:1024 nt
	global_load_dwordx4 v[92:95], v79, s[10:11] offset:2048 nt
	global_load_dwordx4 v[96:99], v79, s[10:11] offset:3072 nt
	s_cmp_eq_u32 s28, 0
	s_cbranch_scc1 .Lp7n_nocol_b2
	s_and_b32 s12, s2, 63
	s_lshl_b32 s12, s12, 10
	s_add_u32 s10, s74, 0x94000
	s_addc_u32 s11, s75, 0
	s_add_u32 s10, s10, s12
	s_addc_u32 s11, s11, 0
	global_load_dwordx4 v[18:21], v79, s[10:11]
	s_add_u32 s10, s10, 0x10000
	s_addc_u32 s11, s11, 0
	global_load_dwordx4 v[22:25], v79, s[10:11]

.Lp7n_nope_b1:
	v_lshlrev_b32_e32 v180, 16, v148
	v_and_b32_e32 v181, 0xffff0000, v148
	v_lshlrev_b32_e32 v182, 16, v149
	v_and_b32_e32 v183, 0xffff0000, v149
	v_lshlrev_b32_e32 v184, 16, v150
	v_and_b32_e32 v185, 0xffff0000, v150
	v_lshlrev_b32_e32 v186, 16, v151
	v_and_b32_e32 v187, 0xffff0000, v151
	v_lshlrev_b32_e32 v188, 16, v152
	v_and_b32_e32 v189, 0xffff0000, v152
	v_lshlrev_b32_e32 v190, 16, v153
	v_and_b32_e32 v191, 0xffff0000, v153
	v_lshlrev_b32_e32 v192, 16, v154
	v_and_b32_e32 v193, 0xffff0000, v154
	v_lshlrev_b32_e32 v194, 16, v155
	v_and_b32_e32 v195, 0xffff0000, v155
	v_lshlrev_b32_e32 v196, 16, v156
	v_and_b32_e32 v197, 0xffff0000, v156
	v_lshlrev_b32_e32 v198, 16, v157
	v_and_b32_e32 v199, 0xffff0000, v157
	v_lshlrev_b32_e32 v200, 16, v158
	v_and_b32_e32 v201, 0xffff0000, v158
	v_lshlrev_b32_e32 v202, 16, v159
	v_and_b32_e32 v203, 0xffff0000, v159
	v_lshlrev_b32_e32 v204, 16, v160
	v_and_b32_e32 v205, 0xffff0000, v160
	v_lshlrev_b32_e32 v206, 16, v161
	v_and_b32_e32 v207, 0xffff0000, v161
	v_lshlrev_b32_e32 v208, 16, v162
	v_and_b32_e32 v209, 0xffff0000, v162
	v_lshlrev_b32_e32 v210, 16, v163
	v_and_b32_e32 v211, 0xffff0000, v163
	v_lshlrev_b32_e32 v212, 16, v164
	v_and_b32_e32 v213, 0xffff0000, v164
	v_lshlrev_b32_e32 v214, 16, v165
	v_and_b32_e32 v215, 0xffff0000, v165
	v_lshlrev_b32_e32 v216, 16, v166
	v_and_b32_e32 v217, 0xffff0000, v166
	v_lshlrev_b32_e32 v218, 16, v167
	v_and_b32_e32 v219, 0xffff0000, v167
	v_lshlrev_b32_e32 v220, 16, v168
	v_and_b32_e32 v221, 0xffff0000, v168
	v_lshlrev_b32_e32 v222, 16, v169
	v_and_b32_e32 v223, 0xffff0000, v169
	v_lshlrev_b32_e32 v224, 16, v170
	v_and_b32_e32 v225, 0xffff0000, v170
	v_lshlrev_b32_e32 v226, 16, v171
	v_and_b32_e32 v227, 0xffff0000, v171
	v_lshlrev_b32_e32 v228, 16, v172
	v_and_b32_e32 v229, 0xffff0000, v172
	v_lshlrev_b32_e32 v230, 16, v173
	v_and_b32_e32 v231, 0xffff0000, v173
	v_lshlrev_b32_e32 v232, 16, v174
	v_and_b32_e32 v233, 0xffff0000, v174
	v_lshlrev_b32_e32 v234, 16, v175
	v_and_b32_e32 v235, 0xffff0000, v175
	v_lshlrev_b32_e32 v236, 16, v176
	v_and_b32_e32 v237, 0xffff0000, v176
	v_lshlrev_b32_e32 v238, 16, v177
	v_and_b32_e32 v239, 0xffff0000, v177
	v_lshlrev_b32_e32 v240, 16, v178
	v_and_b32_e32 v241, 0xffff0000, v178
	v_lshlrev_b32_e32 v242, 16, v179
	v_and_b32_e32 v243, 0xffff0000, v179
	v_pk_mul_f32 v[148:149], v[180:181], v[180:181]
	v_pk_mul_f32 v[156:157], v[196:197], v[196:197]
	v_pk_mul_f32 v[164:165], v[212:213], v[212:213]
	v_pk_mul_f32 v[172:173], v[228:229], v[228:229]
	v_pk_fma_f32 v[148:149], v[182:183], v[182:183], v[148:149]
	v_pk_fma_f32 v[156:157], v[198:199], v[198:199], v[156:157]
	v_pk_fma_f32 v[164:165], v[214:215], v[214:215], v[164:165]
	v_pk_fma_f32 v[172:173], v[230:231], v[230:231], v[172:173]
	v_pk_fma_f32 v[148:149], v[184:185], v[184:185], v[148:149]
	v_pk_fma_f32 v[156:157], v[200:201], v[200:201], v[156:157]
	v_pk_fma_f32 v[164:165], v[216:217], v[216:217], v[164:165]
	v_pk_fma_f32 v[172:173], v[232:233], v[232:233], v[172:173]
	v_pk_fma_f32 v[148:149], v[186:187], v[186:187], v[148:149]
	v_pk_fma_f32 v[156:157], v[202:203], v[202:203], v[156:157]
	v_pk_fma_f32 v[164:165], v[218:219], v[218:219], v[164:165]
	v_pk_fma_f32 v[172:173], v[234:235], v[234:235], v[172:173]
	v_pk_fma_f32 v[148:149], v[188:189], v[188:189], v[148:149]
	v_pk_fma_f32 v[156:157], v[204:205], v[204:205], v[156:157]
	v_pk_fma_f32 v[164:165], v[220:221], v[220:221], v[164:165]
	v_pk_fma_f32 v[172:173], v[236:237], v[236:237], v[172:173]
	v_pk_fma_f32 v[148:149], v[190:191], v[190:191], v[148:149]
	v_pk_fma_f32 v[156:157], v[206:207], v[206:207], v[156:157]
	v_pk_fma_f32 v[164:165], v[222:223], v[222:223], v[164:165]
	v_pk_fma_f32 v[172:173], v[238:239], v[238:239], v[172:173]
	v_pk_fma_f32 v[148:149], v[192:193], v[192:193], v[148:149]
	v_pk_fma_f32 v[156:157], v[208:209], v[208:209], v[156:157]
	v_pk_fma_f32 v[164:165], v[224:225], v[224:225], v[164:165]
	v_pk_fma_f32 v[172:173], v[240:241], v[240:241], v[172:173]
	v_pk_fma_f32 v[148:149], v[194:195], v[194:195], v[148:149]
	v_pk_fma_f32 v[156:157], v[210:211], v[210:211], v[156:157]
	v_pk_fma_f32 v[164:165], v[226:227], v[226:227], v[164:165]
	v_pk_fma_f32 v[172:173], v[242:243], v[242:243], v[172:173]
	v_add_f32_e32 v148, v148, v149
	v_add_f32_e32 v156, v156, v157
	v_add_f32_e32 v164, v164, v165
	v_add_f32_e32 v172, v172, v173
	v_add_f32_dpp v148, v148, v148 quad_perm:[1,0,3,2] row_mask:0xf bank_mask:0xf
	v_add_f32_dpp v156, v156, v156 quad_perm:[1,0,3,2] row_mask:0xf bank_mask:0xf
	v_add_f32_dpp v164, v164, v164 quad_perm:[1,0,3,2] row_mask:0xf bank_mask:0xf
	v_add_f32_dpp v172, v172, v172 quad_perm:[1,0,3,2] row_mask:0xf bank_mask:0xf
	v_add_f32_dpp v148, v148, v148 quad_perm:[2,3,0,1] row_mask:0xf bank_mask:0xf
	v_add_f32_dpp v156, v156, v156 quad_perm:[2,3,0,1] row_mask:0xf bank_mask:0xf
	v_add_f32_dpp v164, v164, v164 quad_perm:[2,3,0,1] row_mask:0xf bank_mask:0xf
	v_add_f32_dpp v172, v172, v172 quad_perm:[2,3,0,1] row_mask:0xf bank_mask:0xf
	v_add_f32_dpp v148, v148, v148 row_ror:4 row_mask:0xf bank_mask:0xf
	v_add_f32_dpp v156, v156, v156 row_ror:4 row_mask:0xf bank_mask:0xf
	v_add_f32_dpp v164, v164, v164 row_ror:4 row_mask:0xf bank_mask:0xf
	v_add_f32_dpp v172, v172, v172 row_ror:4 row_mask:0xf bank_mask:0xf
	v_add_f32_dpp v148, v148, v148 row_ror:8 row_mask:0xf bank_mask:0xf
	v_add_f32_dpp v156, v156, v156 row_ror:8 row_mask:0xf bank_mask:0xf
	v_add_f32_dpp v164, v164, v164 row_ror:8 row_mask:0xf bank_mask:0xf
	v_add_f32_dpp v172, v172, v172 row_ror:8 row_mask:0xf bank_mask:0xf
	ds_bpermute_b32 v149, v73, v148
	ds_bpermute_b32 v157, v73, v156
	ds_bpermute_b32 v165, v73, v164
	ds_bpermute_b32 v173, v73, v172
	s_waitcnt lgkmcnt(0)
	v_add_f32_e32 v148, v148, v149
	v_add_f32_e32 v156, v156, v157
	v_add_f32_e32 v164, v164, v165
	v_add_f32_e32 v172, v172, v173
	ds_bpermute_b32 v149, v74, v148
	ds_bpermute_b32 v157, v74, v156
	ds_bpermute_b32 v165, v74, v164
	ds_bpermute_b32 v173, v74, v172
	s_waitcnt lgkmcnt(0)
	v_add_f32_e32 v148, v148, v149
	v_add_f32_e32 v156, v156, v157
	v_add_f32_e32 v164, v164, v165
	v_add_f32_e32 v172, v172, v173
	v_fmamk_f32 v148, v148, 0x3a800000, v77
	v_fmamk_f32 v156, v156, 0x3a800000, v77
	v_fmamk_f32 v164, v164, 0x3a800000, v77
	v_fmamk_f32 v172, v172, 0x3a800000, v77
	v_mul_f32_e32 v150, 0x4b800000, v148
	v_cmp_gt_f32_e32 vcc, s26, v148
	s_nop 1
	v_cndmask_b32_e32 v148, v148, v150, vcc
	v_rsq_f32_e32 v148, v148
	s_nop 0
	v_mul_f32_e32 v150, 0x45800000, v148
	v_cndmask_b32_e32 v148, v148, v150, vcc
	v_mul_f32_e32 v158, 0x4b800000, v156
	v_cmp_gt_f32_e32 vcc, s26, v156
	s_nop 1
	v_cndmask_b32_e32 v156, v156, v158, vcc
	v_rsq_f32_e32 v156, v156
	s_nop 0
	v_mul_f32_e32 v158, 0x45800000, v156
	v_cndmask_b32_e32 v156, v156, v158, vcc
	v_mul_f32_e32 v166, 0x4b800000, v164
	v_cmp_gt_f32_e32 vcc, s26, v164
	s_nop 1
	v_cndmask_b32_e32 v164, v164, v166, vcc
	v_rsq_f32_e32 v164, v164
	s_nop 0
	v_mul_f32_e32 v166, 0x45800000, v164
	v_cndmask_b32_e32 v164, v164, v166, vcc
	v_mul_f32_e32 v174, 0x4b800000, v172
	v_cmp_gt_f32_e32 vcc, s26, v172
	s_nop 1
	v_cndmask_b32_e32 v172, v172, v174, vcc
	v_rsq_f32_e32 v172, v172
	s_nop 0
	v_mul_f32_e32 v174, 0x45800000, v172
	v_cndmask_b32_e32 v172, v172, v174, vcc
	s_add_u32 s2, s21, 2
	s_lshl_b32 s2, s2, 12
	s_add_u32 s10, s72, s2
	s_addc_u32 s11, s73, 0
	v_pk_mul_f32 v[180:181], v[180:181], v[148:149] op_sel_hi:[1,0]
	v_pk_mul_f32 v[182:183], v[182:183], v[148:149] op_sel_hi:[1,0]
	v_pk_fma_f32 v[84:85], v[2:3], v[180:181], v[84:85]
	v_pk_fma_f32 v[86:87], v[4:5], v[182:183], v[86:87]
	global_store_dwordx4 v79, v[84:87], s[10:11] offset:0 nt
	v_pk_mul_f32 v[184:185], v[184:185], v[148:149] op_sel_hi:[1,0]
	v_pk_mul_f32 v[186:187], v[186:187], v[148:149] op_sel_hi:[1,0]
	v_pk_fma_f32 v[88:89], v[6:7], v[184:185], v[88:89]
	v_pk_fma_f32 v[90:91], v[8:9], v[186:187], v[90:91]
	global_store_dwordx4 v79, v[88:91], s[10:11] offset:1024 nt
	v_pk_mul_f32 v[188:189], v[188:189], v[148:149] op_sel_hi:[1,0]
	v_pk_mul_f32 v[190:191], v[190:191], v[148:149] op_sel_hi:[1,0]
	v_pk_fma_f32 v[92:93], v[10:11], v[188:189], v[92:93]
	v_pk_fma_f32 v[94:95], v[12:13], v[190:191], v[94:95]
	global_store_dwordx4 v79, v[92:95], s[10:11] offset:2048 nt
	v_pk_mul_f32 v[192:193], v[192:193], v[148:149] op_sel_hi:[1,0]
	v_pk_mul_f32 v[194:195], v[194:195], v[148:149] op_sel_hi:[1,0]
	v_pk_fma_f32 v[96:97], v[14:15], v[192:193], v[96:97]
	v_pk_fma_f32 v[98:99], v[16:17], v[194:195], v[98:99]
	global_store_dwordx4 v79, v[96:99], s[10:11] offset:3072 nt
	s_add_u32 s2, s21, 3
	s_lshl_b32 s2, s2, 12
	s_add_u32 s10, s72, s2
	s_addc_u32 s11, s73, 0
	v_pk_mul_f32 v[196:197], v[196:197], v[156:157] op_sel_hi:[1,0]
	v_pk_mul_f32 v[198:199], v[198:199], v[156:157] op_sel_hi:[1,0]
	v_pk_fma_f32 v[100:101], v[2:3], v[196:197], v[100:101]
	v_pk_fma_f32 v[102:103], v[4:5], v[198:199], v[102:103]
	global_store_dwordx4 v79, v[100:103], s[10:11] offset:0 nt
	v_pk_mul_f32 v[200:201], v[200:201], v[156:157] op_sel_hi:[1,0]
	v_pk_mul_f32 v[202:203], v[202:203], v[156:157] op_sel_hi:[1,0]
	v_pk_fma_f32 v[104:105], v[6:7], v[200:201], v[104:105]
	v_pk_fma_f32 v[106:107], v[8:9], v[202:203], v[106:107]
	global_store_dwordx4 v79, v[104:107], s[10:11] offset:1024 nt
	v_pk_mul_f32 v[204:205], v[204:205], v[156:157] op_sel_hi:[1,0]
	v_pk_mul_f32 v[206:207], v[206:207], v[156:157] op_sel_hi:[1,0]
	v_pk_fma_f32 v[108:109], v[10:11], v[204:205], v[108:109]
	v_pk_fma_f32 v[110:111], v[12:13], v[206:207], v[110:111]
	global_store_dwordx4 v79, v[108:111], s[10:11] offset:2048 nt
	v_pk_mul_f32 v[208:209], v[208:209], v[156:157] op_sel_hi:[1,0]
	v_pk_mul_f32 v[210:211], v[210:211], v[156:157] op_sel_hi:[1,0]
	v_pk_fma_f32 v[112:113], v[14:15], v[208:209], v[112:113]
	v_pk_fma_f32 v[114:115], v[16:17], v[210:211], v[114:115]
	global_store_dwordx4 v79, v[112:115], s[10:11] offset:3072 nt
	s_add_u32 s2, s21, 4
	s_lshl_b32 s2, s2, 12
	s_add_u32 s10, s72, s2
	s_addc_u32 s11, s73, 0
	v_pk_mul_f32 v[212:213], v[212:213], v[164:165] op_sel_hi:[1,0]
	v_pk_mul_f32 v[214:215], v[214:215], v[164:165] op_sel_hi:[1,0]
	v_pk_fma_f32 v[116:117], v[2:3], v[212:213], v[116:117]
	v_pk_fma_f32 v[118:119], v[4:5], v[214:215], v[118:119]
	global_store_dwordx4 v79, v[116:119], s[10:11] offset:0 nt
	v_pk_mul_f32 v[216:217], v[216:217], v[164:165] op_sel_hi:[1,0]
	v_pk_mul_f32 v[218:219], v[218:219], v[164:165] op_sel_hi:[1,0]
	v_pk_fma_f32 v[120:121], v[6:7], v[216:217], v[120:121]
	v_pk_fma_f32 v[122:123], v[8:9], v[218:219], v[122:123]
	global_store_dwordx4 v79, v[120:123], s[10:11] offset:1024 nt
	v_pk_mul_f32 v[220:221], v[220:221], v[164:165] op_sel_hi:[1,0]
	v_pk_mul_f32 v[222:223], v[222:223], v[164:165] op_sel_hi:[1,0]
	v_pk_fma_f32 v[124:125], v[10:11], v[220:221], v[124:125]
	v_pk_fma_f32 v[126:127], v[12:13], v[222:223], v[126:127]
	global_store_dwordx4 v79, v[124:127], s[10:11] offset:2048 nt
	v_pk_mul_f32 v[224:225], v[224:225], v[164:165] op_sel_hi:[1,0]
	v_pk_mul_f32 v[226:227], v[226:227], v[164:165] op_sel_hi:[1,0]
	v_pk_fma_f32 v[128:129], v[14:15], v[224:225], v[128:129]
	v_pk_fma_f32 v[130:131], v[16:17], v[226:227], v[130:131]
	global_store_dwordx4 v79, v[128:131], s[10:11] offset:3072 nt
	s_add_u32 s2, s21, 5
	s_lshl_b32 s2, s2, 12
	s_add_u32 s10, s72, s2
	s_addc_u32 s11, s73, 0
	v_pk_mul_f32 v[228:229], v[228:229], v[172:173] op_sel_hi:[1,0]
	v_pk_mul_f32 v[230:231], v[230:231], v[172:173] op_sel_hi:[1,0]
	v_pk_fma_f32 v[132:133], v[2:3], v[228:229], v[132:133]
	v_pk_fma_f32 v[134:135], v[4:5], v[230:231], v[134:135]
	global_store_dwordx4 v79, v[132:135], s[10:11] offset:0 nt
	v_pk_mul_f32 v[232:233], v[232:233], v[172:173] op_sel_hi:[1,0]
	v_pk_mul_f32 v[234:235], v[234:235], v[172:173] op_sel_hi:[1,0]
	v_pk_fma_f32 v[136:137], v[6:7], v[232:233], v[136:137]
	v_pk_fma_f32 v[138:139], v[8:9], v[234:235], v[138:139]
	global_store_dwordx4 v79, v[136:139], s[10:11] offset:1024 nt
	v_pk_mul_f32 v[236:237], v[236:237], v[172:173] op_sel_hi:[1,0]
	v_pk_mul_f32 v[238:239], v[238:239], v[172:173] op_sel_hi:[1,0]
	v_pk_fma_f32 v[140:141], v[10:11], v[236:237], v[140:141]
	v_pk_fma_f32 v[142:143], v[12:13], v[238:239], v[142:143]
	global_store_dwordx4 v79, v[140:143], s[10:11] offset:2048 nt
	v_pk_mul_f32 v[240:241], v[240:241], v[172:173] op_sel_hi:[1,0]
	v_pk_mul_f32 v[242:243], v[242:243], v[172:173] op_sel_hi:[1,0]
	v_pk_fma_f32 v[144:145], v[14:15], v[240:241], v[144:145]
	v_pk_fma_f32 v[146:147], v[16:17], v[242:243], v[146:147]
	global_store_dwordx4 v79, v[144:147], s[10:11] offset:3072 nt
	s_nop 1
	s_add_u32 s2, s21, 6
	s_mul_i32 s12, s2, 0x3000
	s_add_u32 s10, s74, 0x39c4000
	s_addc_u32 s11, s75, 0
	s_add_u32 s10, s10, s12
	s_addc_u32 s11, s11, 0
	global_load_dwordx2 v[148:149], v80, s[10:11] offset:0 nt
	global_load_dwordx2 v[150:151], v80, s[10:11] offset:512 nt
	global_load_dwordx2 v[152:153], v80, s[10:11] offset:1024 nt
	global_load_dwordx2 v[154:155], v80, s[10:11] offset:1536 nt
	s_cmpk_lt_u32 s2, 0x2000
	s_cselect_b32 s10, s4, s6
	s_cselect_b32 s11, s5, s7
	s_and_b32 s12, s2, 0x1fff
	s_lshl_b32 s12, s12, 12
	s_add_u32 s10, s10, s12
	s_addc_u32 s11, s11, 0
	global_load_dwordx4 v[84:87], v79, s[10:11] offset:0 nt
	global_load_dwordx4 v[88:91], v79, s[10:11] offset:1024 nt
	global_load_dwordx4 v[92:95], v79, s[10:11] offset:2048 nt
	global_load_dwordx4 v[96:99], v79, s[10:11] offset:3072 nt
	s_cmp_eq_u32 s28, 0
	s_cbranch_scc1 .Lp7n_nocol_b6
	s_and_b32 s12, s2, 63
	s_lshl_b32 s12, s12, 10
	s_add_u32 s10, s74, 0x94000
	s_addc_u32 s11, s75, 0
	s_add_u32 s10, s10, s12
	s_addc_u32 s11, s11, 0
	global_load_dwordx4 v[18:21], v79, s[10:11]
	s_add_u32 s10, s10, 0x10000
	s_addc_u32 s11, s11, 0
	global_load_dwordx4 v[22:25], v79, s[10:11]

.Lp7n_nope_b2:
	v_lshlrev_b32_e32 v180, 16, v148
	v_and_b32_e32 v181, 0xffff0000, v148
	v_lshlrev_b32_e32 v182, 16, v149
	v_and_b32_e32 v183, 0xffff0000, v149
	v_lshlrev_b32_e32 v184, 16, v150
	v_and_b32_e32 v185, 0xffff0000, v150
	v_lshlrev_b32_e32 v186, 16, v151
	v_and_b32_e32 v187, 0xffff0000, v151
	v_lshlrev_b32_e32 v188, 16, v152
	v_and_b32_e32 v189, 0xffff0000, v152
	v_lshlrev_b32_e32 v190, 16, v153
	v_and_b32_e32 v191, 0xffff0000, v153
	v_lshlrev_b32_e32 v192, 16, v154
	v_and_b32_e32 v193, 0xffff0000, v154
	v_lshlrev_b32_e32 v194, 16, v155
	v_and_b32_e32 v195, 0xffff0000, v155
	v_lshlrev_b32_e32 v196, 16, v156
	v_and_b32_e32 v197, 0xffff0000, v156
	v_lshlrev_b32_e32 v198, 16, v157
	v_and_b32_e32 v199, 0xffff0000, v157
	v_lshlrev_b32_e32 v200, 16, v158
	v_and_b32_e32 v201, 0xffff0000, v158
	v_lshlrev_b32_e32 v202, 16, v159
	v_and_b32_e32 v203, 0xffff0000, v159
	v_lshlrev_b32_e32 v204, 16, v160
	v_and_b32_e32 v205, 0xffff0000, v160
	v_lshlrev_b32_e32 v206, 16, v161
	v_and_b32_e32 v207, 0xffff0000, v161
	v_lshlrev_b32_e32 v208, 16, v162
	v_and_b32_e32 v209, 0xffff0000, v162
	v_lshlrev_b32_e32 v210, 16, v163
	v_and_b32_e32 v211, 0xffff0000, v163
	v_pk_mul_f32 v[148:149], v[180:181], v[180:181]
	v_pk_mul_f32 v[156:157], v[196:197], v[196:197]
	v_pk_fma_f32 v[148:149], v[182:183], v[182:183], v[148:149]
	v_pk_fma_f32 v[156:157], v[198:199], v[198:199], v[156:157]
	v_pk_fma_f32 v[148:149], v[184:185], v[184:185], v[148:149]
	v_pk_fma_f32 v[156:157], v[200:201], v[200:201], v[156:157]
	v_pk_fma_f32 v[148:149], v[186:187], v[186:187], v[148:149]
	v_pk_fma_f32 v[156:157], v[202:203], v[202:203], v[156:157]
	v_pk_fma_f32 v[148:149], v[188:189], v[188:189], v[148:149]
	v_pk_fma_f32 v[156:157], v[204:205], v[204:205], v[156:157]
	v_pk_fma_f32 v[148:149], v[190:191], v[190:191], v[148:149]
	v_pk_fma_f32 v[156:157], v[206:207], v[206:207], v[156:157]
	v_pk_fma_f32 v[148:149], v[192:193], v[192:193], v[148:149]
	v_pk_fma_f32 v[156:157], v[208:209], v[208:209], v[156:157]
	v_pk_fma_f32 v[148:149], v[194:195], v[194:195], v[148:149]
	v_pk_fma_f32 v[156:157], v[210:211], v[210:211], v[156:157]
	v_add_f32_e32 v148, v148, v149
	v_add_f32_e32 v156, v156, v157
	s_nop 0
	v_add_f32_dpp v148, v148, v148 quad_perm:[1,0,3,2] row_mask:0xf bank_mask:0xf
	v_add_f32_dpp v156, v156, v156 quad_perm:[1,0,3,2] row_mask:0xf bank_mask:0xf
	s_nop 0
	v_add_f32_dpp v148, v148, v148 quad_perm:[2,3,0,1] row_mask:0xf bank_mask:0xf
	v_add_f32_dpp v156, v156, v156 quad_perm:[2,3,0,1] row_mask:0xf bank_mask:0xf
	s_nop 0
	v_add_f32_dpp v148, v148, v148 row_ror:4 row_mask:0xf bank_mask:0xf
	v_add_f32_dpp v156, v156, v156 row_ror:4 row_mask:0xf bank_mask:0xf
	s_nop 0
	v_add_f32_dpp v148, v148, v148 row_ror:8 row_mask:0xf bank_mask:0xf
	v_add_f32_dpp v156, v156, v156 row_ror:8 row_mask:0xf bank_mask:0xf
	s_nop 0
	ds_bpermute_b32 v149, v73, v148
	ds_bpermute_b32 v157, v73, v156
	s_waitcnt lgkmcnt(0)
	v_add_f32_e32 v148, v148, v149
	v_add_f32_e32 v156, v156, v157
	ds_bpermute_b32 v149, v74, v148
	ds_bpermute_b32 v157, v74, v156
	s_waitcnt lgkmcnt(0)
	v_add_f32_e32 v148, v148, v149
	v_add_f32_e32 v156, v156, v157
	v_fmamk_f32 v148, v148, 0x3a800000, v77
	v_fmamk_f32 v156, v156, 0x3a800000, v77
	v_mul_f32_e32 v150, 0x4b800000, v148
	v_cmp_gt_f32_e32 vcc, s26, v148
	s_nop 1
	v_cndmask_b32_e32 v148, v148, v150, vcc
	v_rsq_f32_e32 v148, v148
	s_nop 0
	v_mul_f32_e32 v150, 0x45800000, v148
	v_cndmask_b32_e32 v148, v148, v150, vcc
	v_mul_f32_e32 v158, 0x4b800000, v156
	v_cmp_gt_f32_e32 vcc, s26, v156
	s_nop 1
	v_cndmask_b32_e32 v156, v156, v158, vcc
	v_rsq_f32_e32 v156, v156
	s_nop 0
	v_mul_f32_e32 v158, 0x45800000, v156
	v_cndmask_b32_e32 v156, v156, v158, vcc
	s_add_u32 s2, s21, 6
	s_lshl_b32 s2, s2, 12
	s_add_u32 s10, s72, s2
	s_addc_u32 s11, s73, 0
	v_pk_mul_f32 v[180:181], v[180:181], v[148:149] op_sel_hi:[1,0]
	v_pk_mul_f32 v[182:183], v[182:183], v[148:149] op_sel_hi:[1,0]
	v_pk_fma_f32 v[84:85], v[2:3], v[180:181], v[84:85]
	v_pk_fma_f32 v[86:87], v[4:5], v[182:183], v[86:87]
	global_store_dwordx4 v79, v[84:87], s[10:11] offset:0 nt
	v_pk_mul_f32 v[184:185], v[184:185], v[148:149] op_sel_hi:[1,0]
	v_pk_mul_f32 v[186:187], v[186:187], v[148:149] op_sel_hi:[1,0]
	v_pk_fma_f32 v[88:89], v[6:7], v[184:185], v[88:89]
	v_pk_fma_f32 v[90:91], v[8:9], v[186:187], v[90:91]
	global_store_dwordx4 v79, v[88:91], s[10:11] offset:1024 nt
	v_pk_mul_f32 v[188:189], v[188:189], v[148:149] op_sel_hi:[1,0]
	v_pk_mul_f32 v[190:191], v[190:191], v[148:149] op_sel_hi:[1,0]
	v_pk_fma_f32 v[92:93], v[10:11], v[188:189], v[92:93]
	v_pk_fma_f32 v[94:95], v[12:13], v[190:191], v[94:95]
	global_store_dwordx4 v79, v[92:95], s[10:11] offset:2048 nt
	v_pk_mul_f32 v[192:193], v[192:193], v[148:149] op_sel_hi:[1,0]
	v_pk_mul_f32 v[194:195], v[194:195], v[148:149] op_sel_hi:[1,0]
	v_pk_fma_f32 v[96:97], v[14:15], v[192:193], v[96:97]
	v_pk_fma_f32 v[98:99], v[16:17], v[194:195], v[98:99]
	global_store_dwordx4 v79, v[96:99], s[10:11] offset:3072 nt
	s_add_u32 s2, s21, 7
	s_lshl_b32 s2, s2, 12
	s_add_u32 s10, s72, s2
	s_addc_u32 s11, s73, 0
	v_pk_mul_f32 v[196:197], v[196:197], v[156:157] op_sel_hi:[1,0]
	v_pk_mul_f32 v[198:199], v[198:199], v[156:157] op_sel_hi:[1,0]
	v_pk_fma_f32 v[100:101], v[2:3], v[196:197], v[100:101]
	v_pk_fma_f32 v[102:103], v[4:5], v[198:199], v[102:103]
	global_store_dwordx4 v79, v[100:103], s[10:11] offset:0 nt
	v_pk_mul_f32 v[200:201], v[200:201], v[156:157] op_sel_hi:[1,0]
	v_pk_mul_f32 v[202:203], v[202:203], v[156:157] op_sel_hi:[1,0]
	v_pk_fma_f32 v[104:105], v[6:7], v[200:201], v[104:105]
	v_pk_fma_f32 v[106:107], v[8:9], v[202:203], v[106:107]
	global_store_dwordx4 v79, v[104:107], s[10:11] offset:1024 nt
	v_pk_mul_f32 v[204:205], v[204:205], v[156:157] op_sel_hi:[1,0]
	v_pk_mul_f32 v[206:207], v[206:207], v[156:157] op_sel_hi:[1,0]
	v_pk_fma_f32 v[108:109], v[10:11], v[204:205], v[108:109]
	v_pk_fma_f32 v[110:111], v[12:13], v[206:207], v[110:111]
	global_store_dwordx4 v79, v[108:111], s[10:11] offset:2048 nt
	v_pk_mul_f32 v[208:209], v[208:209], v[156:157] op_sel_hi:[1,0]
	v_pk_mul_f32 v[210:211], v[210:211], v[156:157] op_sel_hi:[1,0]
	v_pk_fma_f32 v[112:113], v[14:15], v[208:209], v[112:113]
	v_pk_fma_f32 v[114:115], v[16:17], v[210:211], v[114:115]
	global_store_dwordx4 v79, v[112:115], s[10:11] offset:3072 nt
	s_nop 1
	s_branch .LBB0_1002
